# packed-zeroing version + priority drop issued in the shadow of the last MFMA of each MMA block so the hand-off barrier arrival directly follows the last MFMA
# speedup vs baseline: 1.0131x; 1.0094x over previous
; #define PG8_STAGE(bufoff, gbase, voff) do { _Pragma("unroll") for (int _i = 0; _i < 2; ++_i) \
;         __builtin_amdgcn_global_load_lds((const unsigned*)((const char*)(gbase) + (voff)[_i]), (PG8_LAS unsigned*)(lds + (bufoff) + ldsw + _i * 8192), 16, 0, 0); } while (0)
; #define PG8_LDA(dst, b, h) do { _Pragma("unroll") for (int m = 0; m < 4; ++m) _Pragma("unroll") for (int k = 0; k < 2; ++k) dst[m][k] = *(const PG8_LAS bf16x8*)(lds + PG8_SA(b, h) + aoff + m * 2048 + k * 1024); } while (0)
; #define PG8_LDB(dst, b, h) do { _Pragma("unroll") for (int n = 0; n < 2; ++n) _Pragma("unroll") for (int k = 0; k < 2; ++k) dst[n][k] = *(const PG8_LAS bf16x8*)(lds + PG8_SB(b, h) + boff + n * 2048 + k * 1024); } while (0)
; #define PG8_MMA(ai, bj, At, Bt) do { __builtin_amdgcn_s_setprio(1); _Pragma("unroll") for (int m = 0; m < 4; ++m) _Pragma("unroll") for (int n = 0; n < 2; ++n) _Pragma("unroll") for (int k = 0; k < 2; ++k) \
;         acc[ai][bj][m][n] = __builtin_amdgcn_mfma_f32_16x16x32_bf16(Bt[n][k], At[m][k], acc[ai][bj][m][n], 0, 0, 0); __builtin_amdgcn_s_setprio(0); } while (0)
; #define PG8_BAR __builtin_amdgcn_s_barrier()
; template <class Epi, class Sched, bool ALIGN_EPI = false, bool SP2 = false>
; __device__ __forceinline__ void gemm_phase(PG8_LAS unsigned char* lds, const Gemm g, const Sched& S, const Epi& E) {
;     ...
;         const bool has_next = S.next(ui + 1, nxt);
;         const char* nA = has_next ? (const char*)g.A + (size_t)nxt.pm * tstep : cA; const char* nB = has_next ? (const char*)g.Bt + (size_t)nxt.pn * tstep : cB;
;         for (int t = 0; t < nt; t += 2) {
;             const bool last = (t == nt - 2);
;             const char* a1 = cA + (size_t)(t + 1) * kstep;
;             const char* a2 = last ? nA : cA + (size_t)(t + 2) * kstep; const char* b2 = last ? nB : cB + (size_t)(t + 2) * kstep;
;             const char* a3 = a2 + kstep; const char* b3 = b2 + kstep;
;             if (last && has_next) S.a_ready(nxt);
;             if constexpr (SP2) {
;             PG8_LDB(B0, 0, 0); PG8_LDB(B1, 0, 1); PG8_SCHED; PG8_LDA(At, 0, 0); PG8_STAGE(PG8_SA(1, 1), a1 + hstep, voffA);
;             PG8_WAIT_V(8); PG8_WAIT_L(0); PG8_BAR; PG8_MMA(0, 0, At, B0); PG8_MMA(0, 1, At, B1); PG8_BAR; PG8_SCHED;
;             PG8_LDA(At, 0, 1); PG8_STAGE(PG8_SB(0, 0), b2, voffB); PG8_STAGE(PG8_SB(0, 1), b2 + hstep, voffB); PG8_STAGE(PG8_SA(0, 0), a2, voffA);
.LBB0_57:
	s_add_u32 s46, s44, 0xfff80080
	s_addc_u32 s47, s45, -1
	s_add_i32 s57, 0, 0x10000
	s_cmp_eq_u32 s56, 28
	s_cselect_b32 s49, s17, s47
	s_cselect_b32 s48, s25, s46
	v_add_u32_e32 v148, s57, v151
	s_cselect_b32 s47, s15, s55
	s_cselect_b32 s46, s43, s54
	s_add_i32 s60, 0, 0x14000
	ds_read_b128 v[140:143], v148
	ds_read_b128 v[144:147], v148 offset:1024
	ds_read_b128 v[174:177], v148 offset:2048
	ds_read_b128 v[178:181], v148 offset:3072
	v_add_u32_e32 v148, s60, v151
	ds_read_b128 v[182:185], v148
	ds_read_b128 v[186:189], v148 offset:1024
	ds_read_b128 v[190:193], v148 offset:2048
	ds_read_b128 v[194:197], v148 offset:3072
	v_lshl_add_u64 v[148:149], s[44:45], 0, v[136:137]
	s_add_i32 m0, s28, 0xc000
	ds_read_b128 v[198:201], v172
	ds_read_b128 v[202:205], v172 offset:1024
	ds_read_b128 v[206:209], v172 offset:2048
	ds_read_b128 v[210:213], v172 offset:3072
	ds_read_b128 v[220:223], v172 offset:4096
	ds_read_b128 v[224:227], v172 offset:5120
	ds_read_b128 v[228:231], v172 offset:6144
	ds_read_b128 v[232:235], v172 offset:7168
	global_load_lds_dwordx4 v[148:149], off
	v_lshl_add_u64 v[148:149], s[44:45], 0, v[138:139]
	s_add_i32 m0, s28, 0xe000
	s_nop 0
	global_load_lds_dwordx4 v[148:149], off
	s_waitcnt vmcnt(8)
	s_waitcnt lgkmcnt(0)
	s_setprio 1
	s_barrier
	v_mfma_f32_16x16x32_bf16 v[124:127], v[140:143], v[198:201], v[124:127]
	v_mfma_f32_16x16x32_bf16 v[120:123], v[174:177], v[198:201], v[120:123]
	v_mfma_f32_16x16x32_bf16 v[116:119], v[140:143], v[206:209], v[116:119]
	v_mfma_f32_16x16x32_bf16 v[112:115], v[174:177], v[206:209], v[112:115]
	v_mfma_f32_16x16x32_bf16 v[100:103], v[140:143], v[220:223], v[100:103]
	v_mfma_f32_16x16x32_bf16 v[96:99], v[174:177], v[220:223], v[96:99]
	v_mfma_f32_16x16x32_bf16 v[84:87], v[140:143], v[228:231], v[84:87]
	v_mfma_f32_16x16x32_bf16 v[80:83], v[174:177], v[228:231], v[80:83]
	v_mfma_f32_16x16x32_bf16 v[124:127], v[144:147], v[202:205], v[124:127]
	v_mfma_f32_16x16x32_bf16 v[120:123], v[178:181], v[202:205], v[120:123]
	v_mfma_f32_16x16x32_bf16 v[116:119], v[144:147], v[210:213], v[116:119]
	v_mfma_f32_16x16x32_bf16 v[112:115], v[178:181], v[210:213], v[112:115]
	v_mfma_f32_16x16x32_bf16 v[100:103], v[144:147], v[224:227], v[100:103]
	v_mfma_f32_16x16x32_bf16 v[96:99], v[178:181], v[224:227], v[96:99]
	v_mfma_f32_16x16x32_bf16 v[84:87], v[144:147], v[232:235], v[84:87]
	v_mfma_f32_16x16x32_bf16 v[80:83], v[178:181], v[232:235], v[80:83]
	v_mfma_f32_16x16x32_bf16 v[108:111], v[182:185], v[198:201], v[108:111]
	v_mfma_f32_16x16x32_bf16 v[104:107], v[190:193], v[198:201], v[104:107]
	v_mfma_f32_16x16x32_bf16 v[92:95], v[182:185], v[206:209], v[92:95]
	v_mfma_f32_16x16x32_bf16 v[88:91], v[190:193], v[206:209], v[88:91]
	v_mfma_f32_16x16x32_bf16 v[76:79], v[182:185], v[220:223], v[76:79]
	v_mfma_f32_16x16x32_bf16 v[72:75], v[190:193], v[220:223], v[72:75]
	v_mfma_f32_16x16x32_bf16 v[68:71], v[182:185], v[228:231], v[68:71]
	v_mfma_f32_16x16x32_bf16 v[64:67], v[190:193], v[228:231], v[64:67]
	v_mfma_f32_16x16x32_bf16 v[108:111], v[186:189], v[202:205], v[108:111]
	v_mfma_f32_16x16x32_bf16 v[104:107], v[194:197], v[202:205], v[104:107]
	v_mfma_f32_16x16x32_bf16 v[92:95], v[186:189], v[210:213], v[92:95]
	v_mfma_f32_16x16x32_bf16 v[88:91], v[194:197], v[210:213], v[88:91]
	v_mfma_f32_16x16x32_bf16 v[76:79], v[186:189], v[224:227], v[76:79]
	v_mfma_f32_16x16x32_bf16 v[72:75], v[194:197], v[224:227], v[72:75]
	v_mfma_f32_16x16x32_bf16 v[68:71], v[186:189], v[232:235], v[68:71]
	s_setprio 0
	v_mfma_f32_16x16x32_bf16 v[64:67], v[194:197], v[232:235], v[64:67]
	s_barrier
	s_add_i32 s57, s57, s26
	v_lshl_add_u64 v[148:149], s[46:47], 0, v[132:133]
	s_mov_b32 m0, s57
	ds_read_b128 v[198:201], v172 offset:16384
	ds_read_b128 v[202:205], v172 offset:17408
	ds_read_b128 v[206:209], v172 offset:18432
	ds_read_b128 v[210:213], v172 offset:19456
	ds_read_b128 v[220:223], v172 offset:20480
	ds_read_b128 v[224:227], v172 offset:21504
	ds_read_b128 v[228:231], v172 offset:22528
	ds_read_b128 v[232:235], v172 offset:23552
	global_load_lds_dwordx4 v[148:149], off
	s_add_i32 m0, s57, 0x2000
	s_add_u32 s58, s46, 0x80000
	v_lshl_add_u64 v[214:215], s[46:47], 0, v[128:129]
	s_addc_u32 s59, s47, 0
	s_add_i32 s57, s60, s26
	global_load_lds_dwordx4 v[214:215], off
	v_lshl_add_u64 v[236:237], s[58:59], 0, v[132:133]
	s_mov_b32 m0, s57
	v_lshl_add_u64 v[238:239], s[48:49], 0, v[130:131]
	global_load_lds_dwordx4 v[236:237], off
	v_lshl_add_u64 v[236:237], s[58:59], 0, v[128:129]
	s_add_i32 m0, s57, 0x2000
	s_nop 0
	global_load_lds_dwordx4 v[236:237], off
	v_lshl_add_u64 v[236:237], s[48:49], 0, v[134:135]
	s_mov_b32 m0, s28
	s_nop 0
	global_load_lds_dwordx4 v[236:237], off
	s_mov_b32 m0, s29
	s_nop 0
	global_load_lds_dwordx4 v[238:239], off
	s_waitcnt vmcnt(8)
	s_waitcnt lgkmcnt(0)
	s_setprio 1
	s_barrier
; #define PG8_STAGE(bufoff, gbase, voff) do { _Pragma("unroll") for (int _i = 0; _i < 2; ++_i) \
;         __builtin_amdgcn_global_load_lds((const unsigned*)((const char*)(gbase) + (voff)[_i]), (PG8_LAS unsigned*)(lds + (bufoff) + ldsw + _i * 8192), 16, 0, 0); } while (0)
; #define PG8_LDA(dst, b, h) do { _Pragma("unroll") for (int m = 0; m < 4; ++m) _Pragma("unroll") for (int k = 0; k < 2; ++k) dst[m][k] = *(const PG8_LAS bf16x8*)(lds + PG8_SA(b, h) + aoff + m * 2048 + k * 1024); } while (0)
; #define PG8_LDB(dst, b, h) do { _Pragma("unroll") for (int n = 0; n < 2; ++n) _Pragma("unroll") for (int k = 0; k < 2; ++k) dst[n][k] = *(const PG8_LAS bf16x8*)(lds + PG8_SB(b, h) + boff + n * 2048 + k * 1024); } while (0)
; #define PG8_MMA(ai, bj, At, Bt) do { __builtin_amdgcn_s_setprio(1); _Pragma("unroll") for (int m = 0; m < 4; ++m) _Pragma("unroll") for (int n = 0; n < 2; ++n) _Pragma("unroll") for (int k = 0; k < 2; ++k) \
;         acc[ai][bj][m][n] = __builtin_amdgcn_mfma_f32_16x16x32_bf16(Bt[n][k], At[m][k], acc[ai][bj][m][n], 0, 0, 0); __builtin_amdgcn_s_setprio(0); } while (0)
; #define PG8_WAIT_V(n) asm volatile("s_waitcnt vmcnt(" #n ")" ::: "memory")
; #define PG8_WAIT_L(n) asm volatile("s_waitcnt lgkmcnt(" #n ")" ::: "memory")
; #define PG8_BAR __builtin_amdgcn_s_barrier()
; #define PG8_SCHED __builtin_amdgcn_sched_barrier(0)
; template <class Epi, class Sched, bool ALIGN_EPI = false, bool SP2 = false>
; __device__ __forceinline__ void gemm_phase(PG8_LAS unsigned char* lds, const Gemm g, const Sched& S, const Epi& E) {
;     ...
;             PG8_WAIT_V(8); PG8_WAIT_L(0); PG8_BAR; PG8_MMA(1, 0, At, B0); PG8_MMA(1, 1, At, B1); PG8_BAR; PG8_SCHED;
;             PG8_LDB(B0, 1, 0); PG8_LDB(B1, 1, 1); PG8_SCHED; PG8_LDA(At, 1, 0); PG8_STAGE(PG8_SA(0, 1), a2 + hstep, voffA);
;             PG8_WAIT_V(8); PG8_WAIT_L(0); PG8_BAR; PG8_MMA(0, 0, At, B0); PG8_MMA(0, 1, At, B1); PG8_BAR; PG8_SCHED;
	v_mfma_f32_16x16x32_bf16 v[60:63], v[140:143], v[198:201], v[60:63]
	v_mfma_f32_16x16x32_bf16 v[56:59], v[174:177], v[198:201], v[56:59]
	v_mfma_f32_16x16x32_bf16 v[52:55], v[140:143], v[206:209], v[52:55]
	v_mfma_f32_16x16x32_bf16 v[48:51], v[174:177], v[206:209], v[48:51]
	v_mfma_f32_16x16x32_bf16 v[36:39], v[140:143], v[220:223], v[36:39]
	v_mfma_f32_16x16x32_bf16 v[32:35], v[174:177], v[220:223], v[32:35]
	v_mfma_f32_16x16x32_bf16 v[20:23], v[140:143], v[228:231], v[20:23]
	v_mfma_f32_16x16x32_bf16 v[16:19], v[174:177], v[228:231], v[16:19]
	v_mfma_f32_16x16x32_bf16 v[60:63], v[144:147], v[202:205], v[60:63]
	v_mfma_f32_16x16x32_bf16 v[56:59], v[178:181], v[202:205], v[56:59]
	v_mfma_f32_16x16x32_bf16 v[52:55], v[144:147], v[210:213], v[52:55]
	v_mfma_f32_16x16x32_bf16 v[48:51], v[178:181], v[210:213], v[48:51]
	v_mfma_f32_16x16x32_bf16 v[36:39], v[144:147], v[224:227], v[36:39]
	v_mfma_f32_16x16x32_bf16 v[32:35], v[178:181], v[224:227], v[32:35]
	v_mfma_f32_16x16x32_bf16 v[20:23], v[144:147], v[232:235], v[20:23]
	v_mfma_f32_16x16x32_bf16 v[16:19], v[178:181], v[232:235], v[16:19]
	v_mfma_f32_16x16x32_bf16 v[44:47], v[182:185], v[198:201], v[44:47]
	v_mfma_f32_16x16x32_bf16 v[40:43], v[190:193], v[198:201], v[40:43]
	v_mfma_f32_16x16x32_bf16 v[28:31], v[182:185], v[206:209], v[28:31]
	v_mfma_f32_16x16x32_bf16 v[24:27], v[190:193], v[206:209], v[24:27]
	v_mfma_f32_16x16x32_bf16 v[12:15], v[182:185], v[220:223], v[12:15]
	v_mfma_f32_16x16x32_bf16 v[8:11], v[190:193], v[220:223], v[8:11]
	v_mfma_f32_16x16x32_bf16 v[4:7], v[182:185], v[228:231], v[4:7]
	v_mfma_f32_16x16x32_bf16 v[0:3], v[190:193], v[228:231], v[0:3]
	v_mfma_f32_16x16x32_bf16 v[44:47], v[186:189], v[202:205], v[44:47]
	v_mfma_f32_16x16x32_bf16 v[40:43], v[194:197], v[202:205], v[40:43]
	v_mfma_f32_16x16x32_bf16 v[28:31], v[186:189], v[210:213], v[28:31]
	v_mfma_f32_16x16x32_bf16 v[24:27], v[194:197], v[210:213], v[24:27]
	v_mfma_f32_16x16x32_bf16 v[12:15], v[186:189], v[224:227], v[12:15]
	v_mfma_f32_16x16x32_bf16 v[8:11], v[194:197], v[224:227], v[8:11]
	v_mfma_f32_16x16x32_bf16 v[4:7], v[186:189], v[232:235], v[4:7]
	s_setprio 0
	v_mfma_f32_16x16x32_bf16 v[0:3], v[194:197], v[232:235], v[0:3]
	s_barrier
	s_add_i32 s57, 0, 0x18000
	v_add_u32_e32 v152, s57, v151
	s_add_i32 s58, 0, 0x1c000
	ds_read_b128 v[140:143], v152
	ds_read_b128 v[144:147], v152 offset:1024
	ds_read_b128 v[174:177], v152 offset:2048
	ds_read_b128 v[178:181], v152 offset:3072
	v_add_u32_e32 v152, s58, v151
	ds_read_b128 v[182:185], v152
	ds_read_b128 v[186:189], v152 offset:1024
	ds_read_b128 v[190:193], v152 offset:2048
	ds_read_b128 v[194:197], v152 offset:3072
	s_add_u32 s48, s48, 0x80000
	s_addc_u32 s49, s49, 0
	s_mov_b32 m0, s33
	v_lshl_add_u64 v[240:241], s[48:49], 0, v[134:135]
	ds_read_b128 v[198:201], v172 offset:32768
	ds_read_b128 v[202:205], v172 offset:33792
	ds_read_b128 v[206:209], v172 offset:34816
	ds_read_b128 v[210:213], v172 offset:35840
	ds_read_b128 v[220:223], v172 offset:36864
	ds_read_b128 v[224:227], v172 offset:37888
	ds_read_b128 v[228:231], v172 offset:38912
	ds_read_b128 v[232:235], v172 offset:39936
	global_load_lds_dwordx4 v[240:241], off
	v_lshl_add_u64 v[240:241], s[48:49], 0, v[130:131]
	s_mov_b32 m0, s50
	s_nop 0
	global_load_lds_dwordx4 v[240:241], off
	s_waitcnt vmcnt(8)
	s_waitcnt lgkmcnt(0)
	s_setprio 1
	s_barrier
	v_mfma_f32_16x16x32_bf16 v[124:127], v[140:143], v[198:201], v[124:127]
	v_mfma_f32_16x16x32_bf16 v[120:123], v[174:177], v[198:201], v[120:123]
	v_mfma_f32_16x16x32_bf16 v[116:119], v[140:143], v[206:209], v[116:119]
	v_mfma_f32_16x16x32_bf16 v[112:115], v[174:177], v[206:209], v[112:115]
	v_mfma_f32_16x16x32_bf16 v[100:103], v[140:143], v[220:223], v[100:103]
	v_mfma_f32_16x16x32_bf16 v[96:99], v[174:177], v[220:223], v[96:99]
	v_mfma_f32_16x16x32_bf16 v[84:87], v[140:143], v[228:231], v[84:87]
	v_mfma_f32_16x16x32_bf16 v[80:83], v[174:177], v[228:231], v[80:83]
	v_mfma_f32_16x16x32_bf16 v[124:127], v[144:147], v[202:205], v[124:127]
	v_mfma_f32_16x16x32_bf16 v[120:123], v[178:181], v[202:205], v[120:123]
	v_mfma_f32_16x16x32_bf16 v[116:119], v[144:147], v[210:213], v[116:119]
	v_mfma_f32_16x16x32_bf16 v[112:115], v[178:181], v[210:213], v[112:115]
	v_mfma_f32_16x16x32_bf16 v[100:103], v[144:147], v[224:227], v[100:103]
	v_mfma_f32_16x16x32_bf16 v[96:99], v[178:181], v[224:227], v[96:99]
	v_mfma_f32_16x16x32_bf16 v[84:87], v[144:147], v[232:235], v[84:87]
	v_mfma_f32_16x16x32_bf16 v[80:83], v[178:181], v[232:235], v[80:83]
	v_mfma_f32_16x16x32_bf16 v[108:111], v[182:185], v[198:201], v[108:111]
	v_mfma_f32_16x16x32_bf16 v[104:107], v[190:193], v[198:201], v[104:107]
	v_mfma_f32_16x16x32_bf16 v[92:95], v[182:185], v[206:209], v[92:95]
	v_mfma_f32_16x16x32_bf16 v[88:91], v[190:193], v[206:209], v[88:91]
	v_mfma_f32_16x16x32_bf16 v[76:79], v[182:185], v[220:223], v[76:79]
	v_mfma_f32_16x16x32_bf16 v[72:75], v[190:193], v[220:223], v[72:75]
	v_mfma_f32_16x16x32_bf16 v[68:71], v[182:185], v[228:231], v[68:71]
	v_mfma_f32_16x16x32_bf16 v[64:67], v[190:193], v[228:231], v[64:67]
	v_mfma_f32_16x16x32_bf16 v[108:111], v[186:189], v[202:205], v[108:111]
	v_mfma_f32_16x16x32_bf16 v[104:107], v[194:197], v[202:205], v[104:107]
	v_mfma_f32_16x16x32_bf16 v[92:95], v[186:189], v[210:213], v[92:95]
	v_mfma_f32_16x16x32_bf16 v[88:91], v[194:197], v[210:213], v[88:91]
	v_mfma_f32_16x16x32_bf16 v[76:79], v[186:189], v[224:227], v[76:79]
	v_mfma_f32_16x16x32_bf16 v[72:75], v[194:197], v[224:227], v[72:75]
	v_mfma_f32_16x16x32_bf16 v[68:71], v[186:189], v[232:235], v[68:71]
	s_setprio 0
	v_mfma_f32_16x16x32_bf16 v[64:67], v[194:197], v[232:235], v[64:67]
	s_barrier
; #define PG8_STAGE(bufoff, gbase, voff) do { _Pragma("unroll") for (int _i = 0; _i < 2; ++_i) \
;         __builtin_amdgcn_global_load_lds((const unsigned*)((const char*)(gbase) + (voff)[_i]), (PG8_LAS unsigned*)(lds + (bufoff) + ldsw + _i * 8192), 16, 0, 0); } while (0)
; #define PG8_LDA(dst, b, h) do { _Pragma("unroll") for (int m = 0; m < 4; ++m) _Pragma("unroll") for (int k = 0; k < 2; ++k) dst[m][k] = *(const PG8_LAS bf16x8*)(lds + PG8_SA(b, h) + aoff + m * 2048 + k * 1024); } while (0)
; #define PG8_MMA(ai, bj, At, Bt) do { __builtin_amdgcn_s_setprio(1); _Pragma("unroll") for (int m = 0; m < 4; ++m) _Pragma("unroll") for (int n = 0; n < 2; ++n) _Pragma("unroll") for (int k = 0; k < 2; ++k) \
;         acc[ai][bj][m][n] = __builtin_amdgcn_mfma_f32_16x16x32_bf16(Bt[n][k], At[m][k], acc[ai][bj][m][n], 0, 0, 0); __builtin_amdgcn_s_setprio(0); } while (0)
; #define PG8_WAIT_V(n) asm volatile("s_waitcnt vmcnt(" #n ")" ::: "memory")
; #define PG8_WAIT_L(n) asm volatile("s_waitcnt lgkmcnt(" #n ")" ::: "memory")
; #define PG8_BAR __builtin_amdgcn_s_barrier()
; #define PG8_SCHED __builtin_amdgcn_sched_barrier(0)
; template <class Epi, class Sched, bool ALIGN_EPI = false, bool SP2 = false>
; __device__ __forceinline__ void gemm_phase(PG8_LAS unsigned char* lds, const Gemm g, const Sched& S, const Epi& E) {
;     ...
;         for (int t = 0; t < nt; t += 2) {
;     ...
;             PG8_LDA(At, 1, 1); PG8_STAGE(PG8_SB(1, 0), b3, voffB); PG8_STAGE(PG8_SB(1, 1), b3 + hstep, voffB); PG8_STAGE(PG8_SA(1, 0), a3, voffA);
;             PG8_WAIT_V(8); PG8_WAIT_L(0); PG8_BAR; PG8_MMA(1, 0, At, B0); PG8_MMA(1, 1, At, B1); PG8_BAR; PG8_SCHED;
	s_add_i32 s48, s57, s26
	v_lshl_add_u64 v[148:149], v[148:149], 0, s[90:91]
	s_mov_b32 m0, s48
	ds_read_b128 v[198:201], v172 offset:49152
	ds_read_b128 v[202:205], v172 offset:50176
	ds_read_b128 v[206:209], v172 offset:51200
	ds_read_b128 v[210:213], v172 offset:52224
	ds_read_b128 v[220:223], v172 offset:53248
	ds_read_b128 v[224:227], v172 offset:54272
	ds_read_b128 v[228:231], v172 offset:55296
	ds_read_b128 v[232:235], v172 offset:56320
	global_load_lds_dwordx4 v[148:149], off
	s_add_i32 m0, s48, 0x2000
	s_add_u32 s46, s46, 0x80080
	v_lshl_add_u64 v[148:149], v[214:215], 0, s[90:91]
	s_addc_u32 s47, s47, 0
	s_add_i32 s48, s58, s26
	global_load_lds_dwordx4 v[148:149], off
	v_lshl_add_u64 v[148:149], s[46:47], 0, v[132:133]
	s_mov_b32 m0, s48
	s_nop 0
	global_load_lds_dwordx4 v[148:149], off
	v_lshl_add_u64 v[148:149], s[46:47], 0, v[128:129]
	s_add_i32 m0, s48, 0x2000
	s_nop 0
	global_load_lds_dwordx4 v[148:149], off
	v_lshl_add_u64 v[148:149], v[236:237], 0, s[90:91]
	s_mov_b32 m0, s4
	s_nop 0
	global_load_lds_dwordx4 v[148:149], off
	v_lshl_add_u64 v[148:149], v[238:239], 0, s[90:91]
	s_mov_b32 m0, s51
	s_nop 0
	global_load_lds_dwordx4 v[148:149], off
	s_waitcnt vmcnt(8)
	s_waitcnt lgkmcnt(0)
	s_setprio 1
	s_barrier
	v_mfma_f32_16x16x32_bf16 v[60:63], v[140:143], v[198:201], v[60:63]
	v_mfma_f32_16x16x32_bf16 v[56:59], v[174:177], v[198:201], v[56:59]
	v_mfma_f32_16x16x32_bf16 v[52:55], v[140:143], v[206:209], v[52:55]
	v_mfma_f32_16x16x32_bf16 v[48:51], v[174:177], v[206:209], v[48:51]
	v_mfma_f32_16x16x32_bf16 v[36:39], v[140:143], v[220:223], v[36:39]
	v_mfma_f32_16x16x32_bf16 v[32:35], v[174:177], v[220:223], v[32:35]
	v_mfma_f32_16x16x32_bf16 v[20:23], v[140:143], v[228:231], v[20:23]
	v_mfma_f32_16x16x32_bf16 v[16:19], v[174:177], v[228:231], v[16:19]
	v_mfma_f32_16x16x32_bf16 v[60:63], v[144:147], v[202:205], v[60:63]
	v_mfma_f32_16x16x32_bf16 v[56:59], v[178:181], v[202:205], v[56:59]
	v_mfma_f32_16x16x32_bf16 v[52:55], v[144:147], v[210:213], v[52:55]
	v_mfma_f32_16x16x32_bf16 v[48:51], v[178:181], v[210:213], v[48:51]
	v_mfma_f32_16x16x32_bf16 v[36:39], v[144:147], v[224:227], v[36:39]
	v_mfma_f32_16x16x32_bf16 v[32:35], v[178:181], v[224:227], v[32:35]
	v_mfma_f32_16x16x32_bf16 v[20:23], v[144:147], v[232:235], v[20:23]
	v_mfma_f32_16x16x32_bf16 v[16:19], v[178:181], v[232:235], v[16:19]
	v_mfma_f32_16x16x32_bf16 v[44:47], v[182:185], v[198:201], v[44:47]
	v_mfma_f32_16x16x32_bf16 v[40:43], v[190:193], v[198:201], v[40:43]
	v_mfma_f32_16x16x32_bf16 v[28:31], v[182:185], v[206:209], v[28:31]
	v_mfma_f32_16x16x32_bf16 v[24:27], v[190:193], v[206:209], v[24:27]
	v_mfma_f32_16x16x32_bf16 v[12:15], v[182:185], v[220:223], v[12:15]
	v_mfma_f32_16x16x32_bf16 v[8:11], v[190:193], v[220:223], v[8:11]
	v_mfma_f32_16x16x32_bf16 v[4:7], v[182:185], v[228:231], v[4:7]
	v_mfma_f32_16x16x32_bf16 v[0:3], v[190:193], v[228:231], v[0:3]
	v_mfma_f32_16x16x32_bf16 v[44:47], v[186:189], v[202:205], v[44:47]
	v_mfma_f32_16x16x32_bf16 v[40:43], v[194:197], v[202:205], v[40:43]
	v_mfma_f32_16x16x32_bf16 v[28:31], v[186:189], v[210:213], v[28:31]
	v_mfma_f32_16x16x32_bf16 v[24:27], v[194:197], v[210:213], v[24:27]
	v_mfma_f32_16x16x32_bf16 v[12:15], v[186:189], v[224:227], v[12:15]
	v_mfma_f32_16x16x32_bf16 v[8:11], v[194:197], v[224:227], v[8:11]
	v_mfma_f32_16x16x32_bf16 v[4:7], v[186:189], v[232:235], v[4:7]
	s_setprio 0
	v_mfma_f32_16x16x32_bf16 v[0:3], v[194:197], v[232:235], v[0:3]
	s_barrier
	s_add_i32 s56, s56, 2
	s_add_u32 s44, s44, 0x100
	s_addc_u32 s45, s45, 0
	s_add_u32 s54, s54, 0x100
	s_addc_u32 s55, s55, 0
	s_cmp_gt_u32 s56, 29
	s_cbranch_scc0 .LBB0_57
	s_and_b64 vcc, exec, s[12:13]
	s_cbranch_vccz .LBB0_60
	s_barrier

; #define PG8_STAGE(bufoff, gbase, voff) do { _Pragma("unroll") for (int _i = 0; _i < 2; ++_i) \
;         __builtin_amdgcn_global_load_lds((const unsigned*)((const char*)(gbase) + (voff)[_i]), (PG8_LAS unsigned*)(lds + (bufoff) + ldsw + _i * 8192), 16, 0, 0); } while (0)
; #define PG8_LDA(dst, b, h) do { _Pragma("unroll") for (int m = 0; m < 4; ++m) _Pragma("unroll") for (int k = 0; k < 2; ++k) dst[m][k] = *(const PG8_LAS bf16x8*)(lds + PG8_SA(b, h) + aoff + m * 2048 + k * 1024); } while (0)
; #define PG8_LDB(dst, b, h) do { _Pragma("unroll") for (int n = 0; n < 2; ++n) _Pragma("unroll") for (int k = 0; k < 2; ++k) dst[n][k] = *(const PG8_LAS bf16x8*)(lds + PG8_SB(b, h) + boff + n * 2048 + k * 1024); } while (0)
; #define PG8_MMA(ai, bj, At, Bt) do { __builtin_amdgcn_s_setprio(1); _Pragma("unroll") for (int m = 0; m < 4; ++m) _Pragma("unroll") for (int n = 0; n < 2; ++n) _Pragma("unroll") for (int k = 0; k < 2; ++k) \
;         acc[ai][bj][m][n] = __builtin_amdgcn_mfma_f32_16x16x32_bf16(Bt[n][k], At[m][k], acc[ai][bj][m][n], 0, 0, 0); __builtin_amdgcn_s_setprio(0); } while (0)
; #define PG8_BAR __builtin_amdgcn_s_barrier()
; template <class Epi, class Sched, bool ALIGN_EPI = false, bool SP2 = false>
; __device__ __forceinline__ void gemm_phase(PG8_LAS unsigned char* lds, const Gemm g, const Sched& S, const Epi& E) {
;     ...
;         const bool has_next = S.next(ui + 1, nxt);
;         const char* nA = has_next ? (const char*)g.A + (size_t)nxt.pm * tstep : cA; const char* nB = has_next ? (const char*)g.Bt + (size_t)nxt.pn * tstep : cB;
;         for (int t = 0; t < nt; t += 2) {
;             const bool last = (t == nt - 2);
;             const char* a1 = cA + (size_t)(t + 1) * kstep;
;             const char* a2 = last ? nA : cA + (size_t)(t + 2) * kstep; const char* b2 = last ? nB : cB + (size_t)(t + 2) * kstep;
;             const char* a3 = a2 + kstep; const char* b3 = b2 + kstep;
;             if (last && has_next) S.a_ready(nxt);
;             if constexpr (SP2) {
;             PG8_LDB(B0, 0, 0); PG8_LDB(B1, 0, 1); PG8_SCHED; PG8_LDA(At, 0, 0); PG8_STAGE(PG8_SA(1, 1), a1 + hstep, voffA);
;             PG8_WAIT_V(8); PG8_WAIT_L(0); PG8_BAR; PG8_MMA(0, 0, At, B0); PG8_MMA(0, 1, At, B1); PG8_BAR; PG8_SCHED;
;             PG8_LDA(At, 0, 1); PG8_STAGE(PG8_SB(0, 0), b2, voffB); PG8_STAGE(PG8_SB(0, 1), b2 + hstep, voffB); PG8_STAGE(PG8_SA(0, 0), a2, voffA);
.LBB0_231:
	s_add_u32 s33, s42, 0xfff80080
	s_addc_u32 s44, s43, -1
	s_add_i32 s57, 0, 0x10000
	s_cmp_eq_u32 s29, 28
	s_cselect_b32 s47, s13, s44
	s_cselect_b32 s46, s25, s33
	s_cselect_b32 s45, s11, s28
	s_cselect_b32 s44, s26, s27
	s_add_i32 s33, 0, 0x14000
	v_add_u32_e32 v140, s57, v192
	v_add_u32_e32 v188, s33, v192
	ds_read_b128 v[128:131], v140
	ds_read_b128 v[132:135], v140 offset:1024
	ds_read_b128 v[136:139], v140 offset:2048
	ds_read_b128 v[140:143], v140 offset:3072
	ds_read_b128 v[176:179], v188
	ds_read_b128 v[180:183], v188 offset:1024
	ds_read_b128 v[184:187], v188 offset:2048
	ds_read_b128 v[198:201], v188 offset:3072
	v_lshl_add_u64 v[188:189], s[42:43], 0, v[172:173]
	s_add_i32 m0, s50, 0xc000
	ds_read_b128 v[202:205], v197
	ds_read_b128 v[206:209], v197 offset:1024
	ds_read_b128 v[210:213], v197 offset:2048
	ds_read_b128 v[220:223], v197 offset:3072
	ds_read_b128 v[224:227], v197 offset:4096
	ds_read_b128 v[228:231], v197 offset:5120
	ds_read_b128 v[232:235], v197 offset:6144
	ds_read_b128 v[236:239], v197 offset:7168
	global_load_lds_dwordx4 v[188:189], off
	v_lshl_add_u64 v[188:189], s[42:43], 0, v[174:175]
	s_add_i32 m0, s50, 0xe000
	s_nop 0
	global_load_lds_dwordx4 v[188:189], off
	s_waitcnt vmcnt(8)
	s_waitcnt lgkmcnt(0)
	s_setprio 1
	s_barrier
	v_mfma_f32_16x16x32_bf16 v[124:127], v[128:131], v[202:205], v[124:127]
	v_mfma_f32_16x16x32_bf16 v[120:123], v[136:139], v[202:205], v[120:123]
	v_mfma_f32_16x16x32_bf16 v[116:119], v[128:131], v[210:213], v[116:119]
	v_mfma_f32_16x16x32_bf16 v[112:115], v[136:139], v[210:213], v[112:115]
	v_mfma_f32_16x16x32_bf16 v[100:103], v[128:131], v[224:227], v[100:103]
	v_mfma_f32_16x16x32_bf16 v[96:99], v[136:139], v[224:227], v[96:99]
	v_mfma_f32_16x16x32_bf16 v[84:87], v[128:131], v[232:235], v[84:87]
	v_mfma_f32_16x16x32_bf16 v[80:83], v[136:139], v[232:235], v[80:83]
	v_mfma_f32_16x16x32_bf16 v[124:127], v[132:135], v[206:209], v[124:127]
	v_mfma_f32_16x16x32_bf16 v[120:123], v[140:143], v[206:209], v[120:123]
	v_mfma_f32_16x16x32_bf16 v[116:119], v[132:135], v[220:223], v[116:119]
	v_mfma_f32_16x16x32_bf16 v[112:115], v[140:143], v[220:223], v[112:115]
	v_mfma_f32_16x16x32_bf16 v[100:103], v[132:135], v[228:231], v[100:103]
	v_mfma_f32_16x16x32_bf16 v[96:99], v[140:143], v[228:231], v[96:99]
	v_mfma_f32_16x16x32_bf16 v[84:87], v[132:135], v[236:239], v[84:87]
	v_mfma_f32_16x16x32_bf16 v[80:83], v[140:143], v[236:239], v[80:83]
	v_mfma_f32_16x16x32_bf16 v[108:111], v[176:179], v[202:205], v[108:111]
	v_mfma_f32_16x16x32_bf16 v[104:107], v[184:187], v[202:205], v[104:107]
	v_mfma_f32_16x16x32_bf16 v[92:95], v[176:179], v[210:213], v[92:95]
	v_mfma_f32_16x16x32_bf16 v[88:91], v[184:187], v[210:213], v[88:91]
	v_mfma_f32_16x16x32_bf16 v[76:79], v[176:179], v[224:227], v[76:79]
	v_mfma_f32_16x16x32_bf16 v[72:75], v[184:187], v[224:227], v[72:75]
	v_mfma_f32_16x16x32_bf16 v[68:71], v[176:179], v[232:235], v[68:71]
	v_mfma_f32_16x16x32_bf16 v[64:67], v[184:187], v[232:235], v[64:67]
	v_mfma_f32_16x16x32_bf16 v[108:111], v[180:183], v[206:209], v[108:111]
	v_mfma_f32_16x16x32_bf16 v[104:107], v[198:201], v[206:209], v[104:107]
	v_mfma_f32_16x16x32_bf16 v[92:95], v[180:183], v[220:223], v[92:95]
	v_mfma_f32_16x16x32_bf16 v[88:91], v[198:201], v[220:223], v[88:91]
	v_mfma_f32_16x16x32_bf16 v[76:79], v[180:183], v[228:231], v[76:79]
	v_mfma_f32_16x16x32_bf16 v[72:75], v[198:201], v[228:231], v[72:75]
	v_mfma_f32_16x16x32_bf16 v[68:71], v[180:183], v[236:239], v[68:71]
	s_setprio 0
	v_mfma_f32_16x16x32_bf16 v[64:67], v[198:201], v[236:239], v[64:67]
	s_barrier
	s_add_i32 s57, s57, s48
	v_lshl_add_u64 v[188:189], s[44:45], 0, v[152:153]
	s_mov_b32 m0, s57
	ds_read_b128 v[202:205], v197 offset:16384
	ds_read_b128 v[206:209], v197 offset:17408
	ds_read_b128 v[210:213], v197 offset:18432
	ds_read_b128 v[220:223], v197 offset:19456
	ds_read_b128 v[224:227], v197 offset:20480
	ds_read_b128 v[228:231], v197 offset:21504
	ds_read_b128 v[232:235], v197 offset:22528
	ds_read_b128 v[236:239], v197 offset:23552
	global_load_lds_dwordx4 v[188:189], off
	s_add_i32 m0, s57, 0x2000
	s_add_u32 s58, s44, 0x80000
	v_lshl_add_u64 v[214:215], s[44:45], 0, v[144:145]
	s_addc_u32 s59, s45, 0
	s_add_i32 s33, s33, s48
	global_load_lds_dwordx4 v[214:215], off
	v_lshl_add_u64 v[240:241], s[58:59], 0, v[152:153]
	s_mov_b32 m0, s33
	v_lshl_add_u64 v[242:243], s[46:47], 0, v[146:147]
	global_load_lds_dwordx4 v[240:241], off
	v_lshl_add_u64 v[240:241], s[58:59], 0, v[144:145]
	s_add_i32 m0, s33, 0x2000
	s_nop 0
	global_load_lds_dwordx4 v[240:241], off
	v_lshl_add_u64 v[240:241], s[46:47], 0, v[148:149]
	s_mov_b32 m0, s50
	s_nop 0
	global_load_lds_dwordx4 v[240:241], off
	s_mov_b32 m0, s51
	s_nop 0
	global_load_lds_dwordx4 v[242:243], off
	s_waitcnt vmcnt(8)
	s_waitcnt lgkmcnt(0)
	s_setprio 1
	s_barrier
; #define PG8_STAGE(bufoff, gbase, voff) do { _Pragma("unroll") for (int _i = 0; _i < 2; ++_i) \
;         __builtin_amdgcn_global_load_lds((const unsigned*)((const char*)(gbase) + (voff)[_i]), (PG8_LAS unsigned*)(lds + (bufoff) + ldsw + _i * 8192), 16, 0, 0); } while (0)
; #define PG8_LDA(dst, b, h) do { _Pragma("unroll") for (int m = 0; m < 4; ++m) _Pragma("unroll") for (int k = 0; k < 2; ++k) dst[m][k] = *(const PG8_LAS bf16x8*)(lds + PG8_SA(b, h) + aoff + m * 2048 + k * 1024); } while (0)
; #define PG8_LDB(dst, b, h) do { _Pragma("unroll") for (int n = 0; n < 2; ++n) _Pragma("unroll") for (int k = 0; k < 2; ++k) dst[n][k] = *(const PG8_LAS bf16x8*)(lds + PG8_SB(b, h) + boff + n * 2048 + k * 1024); } while (0)
; #define PG8_MMA(ai, bj, At, Bt) do { __builtin_amdgcn_s_setprio(1); _Pragma("unroll") for (int m = 0; m < 4; ++m) _Pragma("unroll") for (int n = 0; n < 2; ++n) _Pragma("unroll") for (int k = 0; k < 2; ++k) \
;         acc[ai][bj][m][n] = __builtin_amdgcn_mfma_f32_16x16x32_bf16(Bt[n][k], At[m][k], acc[ai][bj][m][n], 0, 0, 0); __builtin_amdgcn_s_setprio(0); } while (0)
; #define PG8_WAIT_V(n) asm volatile("s_waitcnt vmcnt(" #n ")" ::: "memory")
; #define PG8_WAIT_L(n) asm volatile("s_waitcnt lgkmcnt(" #n ")" ::: "memory")
; #define PG8_BAR __builtin_amdgcn_s_barrier()
; #define PG8_SCHED __builtin_amdgcn_sched_barrier(0)
; template <class Epi, class Sched, bool ALIGN_EPI = false, bool SP2 = false>
; __device__ __forceinline__ void gemm_phase(PG8_LAS unsigned char* lds, const Gemm g, const Sched& S, const Epi& E) {
;     ...
;             PG8_WAIT_V(8); PG8_WAIT_L(0); PG8_BAR; PG8_MMA(1, 0, At, B0); PG8_MMA(1, 1, At, B1); PG8_BAR; PG8_SCHED;
;             PG8_LDB(B0, 1, 0); PG8_LDB(B1, 1, 1); PG8_SCHED; PG8_LDA(At, 1, 0); PG8_STAGE(PG8_SA(0, 1), a2 + hstep, voffA);
;             PG8_WAIT_V(8); PG8_WAIT_L(0); PG8_BAR; PG8_MMA(0, 0, At, B0); PG8_MMA(0, 1, At, B1); PG8_BAR; PG8_SCHED;
	v_mfma_f32_16x16x32_bf16 v[60:63], v[128:131], v[202:205], v[60:63]
	v_mfma_f32_16x16x32_bf16 v[56:59], v[136:139], v[202:205], v[56:59]
	v_mfma_f32_16x16x32_bf16 v[52:55], v[128:131], v[210:213], v[52:55]
	v_mfma_f32_16x16x32_bf16 v[48:51], v[136:139], v[210:213], v[48:51]
	v_mfma_f32_16x16x32_bf16 v[36:39], v[128:131], v[224:227], v[36:39]
	v_mfma_f32_16x16x32_bf16 v[32:35], v[136:139], v[224:227], v[32:35]
	v_mfma_f32_16x16x32_bf16 v[20:23], v[128:131], v[232:235], v[20:23]
	v_mfma_f32_16x16x32_bf16 v[16:19], v[136:139], v[232:235], v[16:19]
	v_mfma_f32_16x16x32_bf16 v[60:63], v[132:135], v[206:209], v[60:63]
	v_mfma_f32_16x16x32_bf16 v[56:59], v[140:143], v[206:209], v[56:59]
	v_mfma_f32_16x16x32_bf16 v[52:55], v[132:135], v[220:223], v[52:55]
	v_mfma_f32_16x16x32_bf16 v[48:51], v[140:143], v[220:223], v[48:51]
	v_mfma_f32_16x16x32_bf16 v[36:39], v[132:135], v[228:231], v[36:39]
	v_mfma_f32_16x16x32_bf16 v[32:35], v[140:143], v[228:231], v[32:35]
	v_mfma_f32_16x16x32_bf16 v[20:23], v[132:135], v[236:239], v[20:23]
	v_mfma_f32_16x16x32_bf16 v[16:19], v[140:143], v[236:239], v[16:19]
	v_mfma_f32_16x16x32_bf16 v[44:47], v[176:179], v[202:205], v[44:47]
	v_mfma_f32_16x16x32_bf16 v[40:43], v[184:187], v[202:205], v[40:43]
	v_mfma_f32_16x16x32_bf16 v[28:31], v[176:179], v[210:213], v[28:31]
	v_mfma_f32_16x16x32_bf16 v[24:27], v[184:187], v[210:213], v[24:27]
	v_mfma_f32_16x16x32_bf16 v[12:15], v[176:179], v[224:227], v[12:15]
	v_mfma_f32_16x16x32_bf16 v[8:11], v[184:187], v[224:227], v[8:11]
	v_mfma_f32_16x16x32_bf16 v[4:7], v[176:179], v[232:235], v[4:7]
	v_mfma_f32_16x16x32_bf16 v[0:3], v[184:187], v[232:235], v[0:3]
	v_mfma_f32_16x16x32_bf16 v[44:47], v[180:183], v[206:209], v[44:47]
	v_mfma_f32_16x16x32_bf16 v[40:43], v[198:201], v[206:209], v[40:43]
	v_mfma_f32_16x16x32_bf16 v[28:31], v[180:183], v[220:223], v[28:31]
	v_mfma_f32_16x16x32_bf16 v[24:27], v[198:201], v[220:223], v[24:27]
	v_mfma_f32_16x16x32_bf16 v[12:15], v[180:183], v[228:231], v[12:15]
	v_mfma_f32_16x16x32_bf16 v[8:11], v[198:201], v[228:231], v[8:11]
	v_mfma_f32_16x16x32_bf16 v[4:7], v[180:183], v[236:239], v[4:7]
	s_setprio 0
	v_mfma_f32_16x16x32_bf16 v[0:3], v[198:201], v[236:239], v[0:3]
	s_barrier
	s_add_i32 s33, 0, 0x18000
	s_add_i32 s57, 0, 0x1c000
	v_add_u32_e32 v140, s33, v192
	v_add_u32_e32 v198, s57, v192
	ds_read_b128 v[128:131], v140
	ds_read_b128 v[132:135], v140 offset:1024
	ds_read_b128 v[136:139], v140 offset:2048
	ds_read_b128 v[140:143], v140 offset:3072
	ds_read_b128 v[176:179], v198
	ds_read_b128 v[180:183], v198 offset:1024
	ds_read_b128 v[184:187], v198 offset:2048
	ds_read_b128 v[198:201], v198 offset:3072
	s_add_u32 s46, s46, 0x80000
	s_addc_u32 s47, s47, 0
	s_mov_b32 m0, s52
	v_lshl_add_u64 v[244:245], s[46:47], 0, v[148:149]
	ds_read_b128 v[202:205], v197 offset:32768
	ds_read_b128 v[206:209], v197 offset:33792
	ds_read_b128 v[210:213], v197 offset:34816
	ds_read_b128 v[220:223], v197 offset:35840
	ds_read_b128 v[224:227], v197 offset:36864
	ds_read_b128 v[228:231], v197 offset:37888
	ds_read_b128 v[232:235], v197 offset:38912
	ds_read_b128 v[236:239], v197 offset:39936
	global_load_lds_dwordx4 v[244:245], off
	v_lshl_add_u64 v[244:245], s[46:47], 0, v[146:147]
	s_mov_b32 m0, s53
	s_nop 0
	global_load_lds_dwordx4 v[244:245], off
	s_waitcnt vmcnt(8)
	s_waitcnt lgkmcnt(0)
	s_setprio 1
	s_barrier
	v_mfma_f32_16x16x32_bf16 v[124:127], v[128:131], v[202:205], v[124:127]
	v_mfma_f32_16x16x32_bf16 v[120:123], v[136:139], v[202:205], v[120:123]
	v_mfma_f32_16x16x32_bf16 v[116:119], v[128:131], v[210:213], v[116:119]
	v_mfma_f32_16x16x32_bf16 v[112:115], v[136:139], v[210:213], v[112:115]
	v_mfma_f32_16x16x32_bf16 v[100:103], v[128:131], v[224:227], v[100:103]
	v_mfma_f32_16x16x32_bf16 v[96:99], v[136:139], v[224:227], v[96:99]
	v_mfma_f32_16x16x32_bf16 v[84:87], v[128:131], v[232:235], v[84:87]
	v_mfma_f32_16x16x32_bf16 v[80:83], v[136:139], v[232:235], v[80:83]
	v_mfma_f32_16x16x32_bf16 v[124:127], v[132:135], v[206:209], v[124:127]
	v_mfma_f32_16x16x32_bf16 v[120:123], v[140:143], v[206:209], v[120:123]
	v_mfma_f32_16x16x32_bf16 v[116:119], v[132:135], v[220:223], v[116:119]
	v_mfma_f32_16x16x32_bf16 v[112:115], v[140:143], v[220:223], v[112:115]
	v_mfma_f32_16x16x32_bf16 v[100:103], v[132:135], v[228:231], v[100:103]
	v_mfma_f32_16x16x32_bf16 v[96:99], v[140:143], v[228:231], v[96:99]
	v_mfma_f32_16x16x32_bf16 v[84:87], v[132:135], v[236:239], v[84:87]
	v_mfma_f32_16x16x32_bf16 v[80:83], v[140:143], v[236:239], v[80:83]
	v_mfma_f32_16x16x32_bf16 v[108:111], v[176:179], v[202:205], v[108:111]
	v_mfma_f32_16x16x32_bf16 v[104:107], v[184:187], v[202:205], v[104:107]
	v_mfma_f32_16x16x32_bf16 v[92:95], v[176:179], v[210:213], v[92:95]
	v_mfma_f32_16x16x32_bf16 v[88:91], v[184:187], v[210:213], v[88:91]
	v_mfma_f32_16x16x32_bf16 v[76:79], v[176:179], v[224:227], v[76:79]
	v_mfma_f32_16x16x32_bf16 v[72:75], v[184:187], v[224:227], v[72:75]
	v_mfma_f32_16x16x32_bf16 v[68:71], v[176:179], v[232:235], v[68:71]
	v_mfma_f32_16x16x32_bf16 v[64:67], v[184:187], v[232:235], v[64:67]
	v_mfma_f32_16x16x32_bf16 v[108:111], v[180:183], v[206:209], v[108:111]
	v_mfma_f32_16x16x32_bf16 v[104:107], v[198:201], v[206:209], v[104:107]
	v_mfma_f32_16x16x32_bf16 v[92:95], v[180:183], v[220:223], v[92:95]
	v_mfma_f32_16x16x32_bf16 v[88:91], v[198:201], v[220:223], v[88:91]
	v_mfma_f32_16x16x32_bf16 v[76:79], v[180:183], v[228:231], v[76:79]
	v_mfma_f32_16x16x32_bf16 v[72:75], v[198:201], v[228:231], v[72:75]
	v_mfma_f32_16x16x32_bf16 v[68:71], v[180:183], v[236:239], v[68:71]
	s_setprio 0
	v_mfma_f32_16x16x32_bf16 v[64:67], v[198:201], v[236:239], v[64:67]
	s_barrier
; #define PG8_STAGE(bufoff, gbase, voff) do { _Pragma("unroll") for (int _i = 0; _i < 2; ++_i) \
;         __builtin_amdgcn_global_load_lds((const unsigned*)((const char*)(gbase) + (voff)[_i]), (PG8_LAS unsigned*)(lds + (bufoff) + ldsw + _i * 8192), 16, 0, 0); } while (0)
; #define PG8_LDA(dst, b, h) do { _Pragma("unroll") for (int m = 0; m < 4; ++m) _Pragma("unroll") for (int k = 0; k < 2; ++k) dst[m][k] = *(const PG8_LAS bf16x8*)(lds + PG8_SA(b, h) + aoff + m * 2048 + k * 1024); } while (0)
; #define PG8_MMA(ai, bj, At, Bt) do { __builtin_amdgcn_s_setprio(1); _Pragma("unroll") for (int m = 0; m < 4; ++m) _Pragma("unroll") for (int n = 0; n < 2; ++n) _Pragma("unroll") for (int k = 0; k < 2; ++k) \
;         acc[ai][bj][m][n] = __builtin_amdgcn_mfma_f32_16x16x32_bf16(Bt[n][k], At[m][k], acc[ai][bj][m][n], 0, 0, 0); __builtin_amdgcn_s_setprio(0); } while (0)
; #define PG8_WAIT_V(n) asm volatile("s_waitcnt vmcnt(" #n ")" ::: "memory")
; #define PG8_WAIT_L(n) asm volatile("s_waitcnt lgkmcnt(" #n ")" ::: "memory")
; #define PG8_BAR __builtin_amdgcn_s_barrier()
; #define PG8_SCHED __builtin_amdgcn_sched_barrier(0)
; template <class Epi, class Sched, bool ALIGN_EPI = false, bool SP2 = false>
; __device__ __forceinline__ void gemm_phase(PG8_LAS unsigned char* lds, const Gemm g, const Sched& S, const Epi& E) {
;     ...
;         for (int t = 0; t < nt; t += 2) {
;     ...
;             PG8_LDA(At, 1, 1); PG8_STAGE(PG8_SB(1, 0), b3, voffB); PG8_STAGE(PG8_SB(1, 1), b3 + hstep, voffB); PG8_STAGE(PG8_SA(1, 0), a3, voffA);
;             PG8_WAIT_V(8); PG8_WAIT_L(0); PG8_BAR; PG8_MMA(1, 0, At, B0); PG8_MMA(1, 1, At, B1); PG8_BAR; PG8_SCHED;
	s_add_i32 s33, s33, s48
	v_lshl_add_u64 v[188:189], v[188:189], 0, s[90:91]
	s_mov_b32 m0, s33
	ds_read_b128 v[202:205], v197 offset:49152
	ds_read_b128 v[206:209], v197 offset:50176
	ds_read_b128 v[210:213], v197 offset:51200
	ds_read_b128 v[220:223], v197 offset:52224
	ds_read_b128 v[224:227], v197 offset:53248
	ds_read_b128 v[228:231], v197 offset:54272
	ds_read_b128 v[232:235], v197 offset:55296
	ds_read_b128 v[236:239], v197 offset:56320
	global_load_lds_dwordx4 v[188:189], off
	s_add_i32 m0, s33, 0x2000
	s_add_u32 s44, s44, 0x80080
	v_lshl_add_u64 v[188:189], v[214:215], 0, s[90:91]
	s_addc_u32 s45, s45, 0
	s_add_i32 s33, s57, s48
	global_load_lds_dwordx4 v[188:189], off
	v_lshl_add_u64 v[188:189], s[44:45], 0, v[152:153]
	s_mov_b32 m0, s33
	s_nop 0
	global_load_lds_dwordx4 v[188:189], off
	v_lshl_add_u64 v[188:189], s[44:45], 0, v[144:145]
	s_add_i32 m0, s33, 0x2000
	s_nop 0
	global_load_lds_dwordx4 v[188:189], off
	v_lshl_add_u64 v[188:189], v[240:241], 0, s[90:91]
	s_mov_b32 m0, s4
	s_nop 0
	global_load_lds_dwordx4 v[188:189], off
	v_lshl_add_u64 v[188:189], v[242:243], 0, s[90:91]
	s_mov_b32 m0, s54
	s_nop 0
	global_load_lds_dwordx4 v[188:189], off
	s_waitcnt vmcnt(8)
	s_waitcnt lgkmcnt(0)
	s_setprio 1
	s_barrier
	v_mfma_f32_16x16x32_bf16 v[60:63], v[128:131], v[202:205], v[60:63]
	v_mfma_f32_16x16x32_bf16 v[56:59], v[136:139], v[202:205], v[56:59]
	v_mfma_f32_16x16x32_bf16 v[52:55], v[128:131], v[210:213], v[52:55]
	v_mfma_f32_16x16x32_bf16 v[48:51], v[136:139], v[210:213], v[48:51]
	v_mfma_f32_16x16x32_bf16 v[36:39], v[128:131], v[224:227], v[36:39]
	v_mfma_f32_16x16x32_bf16 v[32:35], v[136:139], v[224:227], v[32:35]
	v_mfma_f32_16x16x32_bf16 v[20:23], v[128:131], v[232:235], v[20:23]
	v_mfma_f32_16x16x32_bf16 v[16:19], v[136:139], v[232:235], v[16:19]
	v_mfma_f32_16x16x32_bf16 v[60:63], v[132:135], v[206:209], v[60:63]
	v_mfma_f32_16x16x32_bf16 v[56:59], v[140:143], v[206:209], v[56:59]
	v_mfma_f32_16x16x32_bf16 v[52:55], v[132:135], v[220:223], v[52:55]
	v_mfma_f32_16x16x32_bf16 v[48:51], v[140:143], v[220:223], v[48:51]
	v_mfma_f32_16x16x32_bf16 v[36:39], v[132:135], v[228:231], v[36:39]
	v_mfma_f32_16x16x32_bf16 v[32:35], v[140:143], v[228:231], v[32:35]
	v_mfma_f32_16x16x32_bf16 v[20:23], v[132:135], v[236:239], v[20:23]
	v_mfma_f32_16x16x32_bf16 v[16:19], v[140:143], v[236:239], v[16:19]
	v_mfma_f32_16x16x32_bf16 v[44:47], v[176:179], v[202:205], v[44:47]
	v_mfma_f32_16x16x32_bf16 v[40:43], v[184:187], v[202:205], v[40:43]
	v_mfma_f32_16x16x32_bf16 v[28:31], v[176:179], v[210:213], v[28:31]
	v_mfma_f32_16x16x32_bf16 v[24:27], v[184:187], v[210:213], v[24:27]
	v_mfma_f32_16x16x32_bf16 v[12:15], v[176:179], v[224:227], v[12:15]
	v_mfma_f32_16x16x32_bf16 v[8:11], v[184:187], v[224:227], v[8:11]
	v_mfma_f32_16x16x32_bf16 v[4:7], v[176:179], v[232:235], v[4:7]
	v_mfma_f32_16x16x32_bf16 v[0:3], v[184:187], v[232:235], v[0:3]
	v_mfma_f32_16x16x32_bf16 v[44:47], v[180:183], v[206:209], v[44:47]
	v_mfma_f32_16x16x32_bf16 v[40:43], v[198:201], v[206:209], v[40:43]
	v_mfma_f32_16x16x32_bf16 v[28:31], v[180:183], v[220:223], v[28:31]
	v_mfma_f32_16x16x32_bf16 v[24:27], v[198:201], v[220:223], v[24:27]
	v_mfma_f32_16x16x32_bf16 v[12:15], v[180:183], v[228:231], v[12:15]
	v_mfma_f32_16x16x32_bf16 v[8:11], v[198:201], v[228:231], v[8:11]
	v_mfma_f32_16x16x32_bf16 v[4:7], v[180:183], v[236:239], v[4:7]
	s_setprio 0
	v_mfma_f32_16x16x32_bf16 v[0:3], v[198:201], v[236:239], v[0:3]
	s_barrier
	s_add_i32 s29, s29, 2
	s_add_u32 s42, s42, 0x100
	s_addc_u32 s43, s43, 0
	s_add_u32 s27, s27, 0x100
	s_addc_u32 s28, s28, 0
	s_cmp_gt_u32 s29, 29
	s_cbranch_scc0 .LBB0_231
	s_and_b64 vcc, exec, s[8:9]
	s_cbranch_vccz .LBB0_234
	s_barrier

; #define PG8_STAGE(bufoff, gbase, voff) do { _Pragma("unroll") for (int _i = 0; _i < 2; ++_i) \
;         __builtin_amdgcn_global_load_lds((const unsigned*)((const char*)(gbase) + (voff)[_i]), (PG8_LAS unsigned*)(lds + (bufoff) + ldsw + _i * 8192), 16, 0, 0); } while (0)
; #define PG8_LDA(dst, b, h) do { _Pragma("unroll") for (int m = 0; m < 4; ++m) _Pragma("unroll") for (int k = 0; k < 2; ++k) dst[m][k] = *(const PG8_LAS bf16x8*)(lds + PG8_SA(b, h) + aoff + m * 2048 + k * 1024); } while (0)
; #define PG8_LDB(dst, b, h) do { _Pragma("unroll") for (int n = 0; n < 2; ++n) _Pragma("unroll") for (int k = 0; k < 2; ++k) dst[n][k] = *(const PG8_LAS bf16x8*)(lds + PG8_SB(b, h) + boff + n * 2048 + k * 1024); } while (0)
; #define PG8_MMA(ai, bj, At, Bt) do { __builtin_amdgcn_s_setprio(1); _Pragma("unroll") for (int m = 0; m < 4; ++m) _Pragma("unroll") for (int n = 0; n < 2; ++n) _Pragma("unroll") for (int k = 0; k < 2; ++k) \
;         acc[ai][bj][m][n] = __builtin_amdgcn_mfma_f32_16x16x32_bf16(Bt[n][k], At[m][k], acc[ai][bj][m][n], 0, 0, 0); __builtin_amdgcn_s_setprio(0); } while (0)
; #define PG8_BAR __builtin_amdgcn_s_barrier()
; template <class Epi, class Sched, bool ALIGN_EPI = false, bool SP2 = false>
; __device__ __forceinline__ void gemm_phase(PG8_LAS unsigned char* lds, const Gemm g, const Sched& S, const Epi& E) {
;     ...
;         const bool has_next = S.next(ui + 1, nxt);
;         const char* nA = has_next ? (const char*)g.A + (size_t)nxt.pm * tstep : cA; const char* nB = has_next ? (const char*)g.Bt + (size_t)nxt.pn * tstep : cB;
;         for (int t = 0; t < nt; t += 2) {
;             const bool last = (t == nt - 2);
;             const char* a1 = cA + (size_t)(t + 1) * kstep;
;             const char* a2 = last ? nA : cA + (size_t)(t + 2) * kstep; const char* b2 = last ? nB : cB + (size_t)(t + 2) * kstep;
;             const char* a3 = a2 + kstep; const char* b3 = b2 + kstep;
;             if (last && has_next) S.a_ready(nxt);
;             if constexpr (SP2) {
;             PG8_LDB(B0, 0, 0); PG8_LDB(B1, 0, 1); PG8_SCHED; PG8_LDA(At, 0, 0); PG8_STAGE(PG8_SA(1, 1), a1 + hstep, voffA);
;             PG8_WAIT_V(8); PG8_WAIT_L(0); PG8_BAR; PG8_MMA(0, 0, At, B0); PG8_MMA(0, 1, At, B1); PG8_BAR; PG8_SCHED;
;             PG8_LDA(At, 0, 1); PG8_STAGE(PG8_SB(0, 0), b2, voffB); PG8_STAGE(PG8_SB(0, 1), b2 + hstep, voffB); PG8_STAGE(PG8_SA(0, 0), a2, voffA);
.LBB0_291:
	s_add_u32 s18, s16, 0x14aba100
	s_addc_u32 s19, s17, 0
	s_add_u32 s44, s16, s41
	s_addc_u32 s45, s17, s42
	s_cmp_eq_u32 s43, 28
	s_cselect_b32 s39, s89, s19
	s_cselect_b32 s38, s88, s18
	s_cselect_b32 s19, s15, s45
	s_cselect_b32 s18, s14, s44
	s_add_i32 s44, 0, 0x10000
	v_add_u32_e32 v150, s44, v140
	s_add_i32 s46, 0, 0x14000
	ds_read_b128 v[142:145], v150
	ds_read_b128 v[146:149], v150 offset:1024
	ds_read_b128 v[170:173], v150 offset:2048
	ds_read_b128 v[174:177], v150 offset:3072
	v_add_u32_e32 v150, s46, v140
	ds_read_b128 v[178:181], v150
	ds_read_b128 v[182:185], v150 offset:1024
	ds_read_b128 v[186:189], v150 offset:2048
	ds_read_b128 v[190:193], v150 offset:3072
	v_lshl_add_u64 v[150:151], s[16:17], 0, v[134:135]
	s_add_i32 m0, s13, 0xc000
	ds_read_b128 v[194:197], v141
	ds_read_b128 v[198:201], v141 offset:1024
	ds_read_b128 v[202:205], v141 offset:2048
	ds_read_b128 v[206:209], v141 offset:3072
	ds_read_b128 v[210:213], v141 offset:4096
	ds_read_b128 v[220:223], v141 offset:5120
	ds_read_b128 v[224:227], v141 offset:6144
	ds_read_b128 v[228:231], v141 offset:7168
	global_load_lds_dwordx4 v[150:151], off
	v_lshl_add_u64 v[150:151], s[16:17], 0, v[136:137]
	s_add_i32 m0, s13, 0xe000
	s_nop 0
	global_load_lds_dwordx4 v[150:151], off
	s_waitcnt vmcnt(8)
	s_waitcnt lgkmcnt(0)
	s_setprio 1
	s_barrier
	v_mfma_f32_16x16x32_bf16 v[124:127], v[142:145], v[194:197], v[124:127]
	v_mfma_f32_16x16x32_bf16 v[120:123], v[170:173], v[194:197], v[120:123]
	v_mfma_f32_16x16x32_bf16 v[108:111], v[142:145], v[202:205], v[108:111]
	v_mfma_f32_16x16x32_bf16 v[104:107], v[170:173], v[202:205], v[104:107]
	v_mfma_f32_16x16x32_bf16 v[92:95], v[142:145], v[210:213], v[92:95]
	v_mfma_f32_16x16x32_bf16 v[88:91], v[170:173], v[210:213], v[88:91]
	v_mfma_f32_16x16x32_bf16 v[76:79], v[142:145], v[224:227], v[76:79]
	v_mfma_f32_16x16x32_bf16 v[72:75], v[170:173], v[224:227], v[72:75]
	v_mfma_f32_16x16x32_bf16 v[124:127], v[146:149], v[198:201], v[124:127]
	v_mfma_f32_16x16x32_bf16 v[120:123], v[174:177], v[198:201], v[120:123]
	v_mfma_f32_16x16x32_bf16 v[108:111], v[146:149], v[206:209], v[108:111]
	v_mfma_f32_16x16x32_bf16 v[104:107], v[174:177], v[206:209], v[104:107]
	v_mfma_f32_16x16x32_bf16 v[92:95], v[146:149], v[220:223], v[92:95]
	v_mfma_f32_16x16x32_bf16 v[88:91], v[174:177], v[220:223], v[88:91]
	v_mfma_f32_16x16x32_bf16 v[76:79], v[146:149], v[228:231], v[76:79]
	v_mfma_f32_16x16x32_bf16 v[72:75], v[174:177], v[228:231], v[72:75]
	v_mfma_f32_16x16x32_bf16 v[116:119], v[178:181], v[194:197], v[116:119]
	v_mfma_f32_16x16x32_bf16 v[112:115], v[186:189], v[194:197], v[112:115]
	v_mfma_f32_16x16x32_bf16 v[100:103], v[178:181], v[202:205], v[100:103]
	v_mfma_f32_16x16x32_bf16 v[96:99], v[186:189], v[202:205], v[96:99]
	v_mfma_f32_16x16x32_bf16 v[84:87], v[178:181], v[210:213], v[84:87]
	v_mfma_f32_16x16x32_bf16 v[80:83], v[186:189], v[210:213], v[80:83]
	v_mfma_f32_16x16x32_bf16 v[68:71], v[178:181], v[224:227], v[68:71]
	v_mfma_f32_16x16x32_bf16 v[64:67], v[186:189], v[224:227], v[64:67]
	v_mfma_f32_16x16x32_bf16 v[116:119], v[182:185], v[198:201], v[116:119]
	v_mfma_f32_16x16x32_bf16 v[112:115], v[190:193], v[198:201], v[112:115]
	v_mfma_f32_16x16x32_bf16 v[100:103], v[182:185], v[206:209], v[100:103]
	v_mfma_f32_16x16x32_bf16 v[96:99], v[190:193], v[206:209], v[96:99]
	v_mfma_f32_16x16x32_bf16 v[84:87], v[182:185], v[220:223], v[84:87]
	v_mfma_f32_16x16x32_bf16 v[80:83], v[190:193], v[220:223], v[80:83]
	v_mfma_f32_16x16x32_bf16 v[68:71], v[182:185], v[228:231], v[68:71]
	s_setprio 0
	v_mfma_f32_16x16x32_bf16 v[64:67], v[190:193], v[228:231], v[64:67]
	s_barrier
	s_add_i32 s44, s44, s26
	v_lshl_add_u64 v[150:151], s[18:19], 0, v[152:153]
	s_mov_b32 m0, s44
	ds_read_b128 v[194:197], v141 offset:16384
	ds_read_b128 v[198:201], v141 offset:17408
	ds_read_b128 v[202:205], v141 offset:18432
	ds_read_b128 v[206:209], v141 offset:19456
	ds_read_b128 v[210:213], v141 offset:20480
	ds_read_b128 v[220:223], v141 offset:21504
	ds_read_b128 v[224:227], v141 offset:22528
	ds_read_b128 v[228:231], v141 offset:23552
	global_load_lds_dwordx4 v[150:151], off
	s_add_i32 m0, s44, 0x2000
	s_add_u32 s44, s18, 0x80000
	v_lshl_add_u64 v[214:215], s[18:19], 0, v[128:129]
	s_addc_u32 s45, s19, 0
	s_add_i32 s46, s46, s26
	global_load_lds_dwordx4 v[214:215], off
	v_lshl_add_u64 v[232:233], s[44:45], 0, v[152:153]
	s_mov_b32 m0, s46
	v_lshl_add_u64 v[234:235], s[38:39], 0, v[130:131]
	global_load_lds_dwordx4 v[232:233], off
	v_lshl_add_u64 v[232:233], s[44:45], 0, v[128:129]
	s_add_i32 m0, s46, 0x2000
	s_nop 0
	global_load_lds_dwordx4 v[232:233], off
	v_lshl_add_u64 v[232:233], s[38:39], 0, v[132:133]
	s_mov_b32 m0, s13
	s_nop 0
	global_load_lds_dwordx4 v[232:233], off
	s_mov_b32 m0, s27
	s_nop 0
	global_load_lds_dwordx4 v[234:235], off
	s_waitcnt vmcnt(8)
	s_waitcnt lgkmcnt(0)
	s_setprio 1
	s_barrier
; #define PG8_STAGE(bufoff, gbase, voff) do { _Pragma("unroll") for (int _i = 0; _i < 2; ++_i) \
;         __builtin_amdgcn_global_load_lds((const unsigned*)((const char*)(gbase) + (voff)[_i]), (PG8_LAS unsigned*)(lds + (bufoff) + ldsw + _i * 8192), 16, 0, 0); } while (0)
; #define PG8_LDA(dst, b, h) do { _Pragma("unroll") for (int m = 0; m < 4; ++m) _Pragma("unroll") for (int k = 0; k < 2; ++k) dst[m][k] = *(const PG8_LAS bf16x8*)(lds + PG8_SA(b, h) + aoff + m * 2048 + k * 1024); } while (0)
; #define PG8_LDB(dst, b, h) do { _Pragma("unroll") for (int n = 0; n < 2; ++n) _Pragma("unroll") for (int k = 0; k < 2; ++k) dst[n][k] = *(const PG8_LAS bf16x8*)(lds + PG8_SB(b, h) + boff + n * 2048 + k * 1024); } while (0)
; #define PG8_MMA(ai, bj, At, Bt) do { __builtin_amdgcn_s_setprio(1); _Pragma("unroll") for (int m = 0; m < 4; ++m) _Pragma("unroll") for (int n = 0; n < 2; ++n) _Pragma("unroll") for (int k = 0; k < 2; ++k) \
;         acc[ai][bj][m][n] = __builtin_amdgcn_mfma_f32_16x16x32_bf16(Bt[n][k], At[m][k], acc[ai][bj][m][n], 0, 0, 0); __builtin_amdgcn_s_setprio(0); } while (0)
; #define PG8_WAIT_V(n) asm volatile("s_waitcnt vmcnt(" #n ")" ::: "memory")
; #define PG8_WAIT_L(n) asm volatile("s_waitcnt lgkmcnt(" #n ")" ::: "memory")
; #define PG8_BAR __builtin_amdgcn_s_barrier()
; #define PG8_SCHED __builtin_amdgcn_sched_barrier(0)
; template <class Epi, class Sched, bool ALIGN_EPI = false, bool SP2 = false>
; __device__ __forceinline__ void gemm_phase(PG8_LAS unsigned char* lds, const Gemm g, const Sched& S, const Epi& E) {
;     ...
;             PG8_WAIT_V(8); PG8_WAIT_L(0); PG8_BAR; PG8_MMA(1, 0, At, B0); PG8_MMA(1, 1, At, B1); PG8_BAR; PG8_SCHED;
;             PG8_LDB(B0, 1, 0); PG8_LDB(B1, 1, 1); PG8_SCHED; PG8_LDA(At, 1, 0); PG8_STAGE(PG8_SA(0, 1), a2 + hstep, voffA);
;             PG8_WAIT_V(8); PG8_WAIT_L(0); PG8_BAR; PG8_MMA(0, 0, At, B0); PG8_MMA(0, 1, At, B1); PG8_BAR; PG8_SCHED;
	v_mfma_f32_16x16x32_bf16 v[60:63], v[142:145], v[194:197], v[60:63]
	v_mfma_f32_16x16x32_bf16 v[56:59], v[170:173], v[194:197], v[56:59]
	v_mfma_f32_16x16x32_bf16 v[44:47], v[142:145], v[202:205], v[44:47]
	v_mfma_f32_16x16x32_bf16 v[40:43], v[170:173], v[202:205], v[40:43]
	v_mfma_f32_16x16x32_bf16 v[28:31], v[142:145], v[210:213], v[28:31]
	v_mfma_f32_16x16x32_bf16 v[24:27], v[170:173], v[210:213], v[24:27]
	v_mfma_f32_16x16x32_bf16 v[12:15], v[142:145], v[224:227], v[12:15]
	v_mfma_f32_16x16x32_bf16 v[8:11], v[170:173], v[224:227], v[8:11]
	v_mfma_f32_16x16x32_bf16 v[60:63], v[146:149], v[198:201], v[60:63]
	v_mfma_f32_16x16x32_bf16 v[56:59], v[174:177], v[198:201], v[56:59]
	v_mfma_f32_16x16x32_bf16 v[44:47], v[146:149], v[206:209], v[44:47]
	v_mfma_f32_16x16x32_bf16 v[40:43], v[174:177], v[206:209], v[40:43]
	v_mfma_f32_16x16x32_bf16 v[28:31], v[146:149], v[220:223], v[28:31]
	v_mfma_f32_16x16x32_bf16 v[24:27], v[174:177], v[220:223], v[24:27]
	v_mfma_f32_16x16x32_bf16 v[12:15], v[146:149], v[228:231], v[12:15]
	v_mfma_f32_16x16x32_bf16 v[8:11], v[174:177], v[228:231], v[8:11]
	v_mfma_f32_16x16x32_bf16 v[52:55], v[178:181], v[194:197], v[52:55]
	v_mfma_f32_16x16x32_bf16 v[48:51], v[186:189], v[194:197], v[48:51]
	v_mfma_f32_16x16x32_bf16 v[36:39], v[178:181], v[202:205], v[36:39]
	v_mfma_f32_16x16x32_bf16 v[32:35], v[186:189], v[202:205], v[32:35]
	v_mfma_f32_16x16x32_bf16 v[20:23], v[178:181], v[210:213], v[20:23]
	v_mfma_f32_16x16x32_bf16 v[16:19], v[186:189], v[210:213], v[16:19]
	v_mfma_f32_16x16x32_bf16 v[4:7], v[178:181], v[224:227], v[4:7]
	v_mfma_f32_16x16x32_bf16 v[0:3], v[186:189], v[224:227], v[0:3]
	v_mfma_f32_16x16x32_bf16 v[52:55], v[182:185], v[198:201], v[52:55]
	v_mfma_f32_16x16x32_bf16 v[48:51], v[190:193], v[198:201], v[48:51]
	v_mfma_f32_16x16x32_bf16 v[36:39], v[182:185], v[206:209], v[36:39]
	v_mfma_f32_16x16x32_bf16 v[32:35], v[190:193], v[206:209], v[32:35]
	v_mfma_f32_16x16x32_bf16 v[20:23], v[182:185], v[220:223], v[20:23]
	v_mfma_f32_16x16x32_bf16 v[16:19], v[190:193], v[220:223], v[16:19]
	v_mfma_f32_16x16x32_bf16 v[4:7], v[182:185], v[228:231], v[4:7]
	s_setprio 0
	v_mfma_f32_16x16x32_bf16 v[0:3], v[190:193], v[228:231], v[0:3]
	s_barrier
	s_add_i32 s44, 0, 0x18000
	s_add_i32 s45, 0, 0x1c000
	v_add_u32_e32 v174, s44, v140
	v_add_u32_e32 v190, s45, v140
	ds_read_b128 v[142:145], v174
	ds_read_b128 v[146:149], v174 offset:1024
	ds_read_b128 v[170:173], v174 offset:2048
	ds_read_b128 v[174:177], v174 offset:3072
	ds_read_b128 v[178:181], v190
	ds_read_b128 v[182:185], v190 offset:1024
	ds_read_b128 v[186:189], v190 offset:2048
	ds_read_b128 v[190:193], v190 offset:3072
	s_add_u32 s38, s38, 0x80000
	s_addc_u32 s39, s39, 0
	s_mov_b32 m0, s28
	v_lshl_add_u64 v[236:237], s[38:39], 0, v[132:133]
	ds_read_b128 v[194:197], v141 offset:32768
	ds_read_b128 v[198:201], v141 offset:33792
	ds_read_b128 v[202:205], v141 offset:34816
	ds_read_b128 v[206:209], v141 offset:35840
	ds_read_b128 v[210:213], v141 offset:36864
	ds_read_b128 v[220:223], v141 offset:37888
	ds_read_b128 v[224:227], v141 offset:38912
	ds_read_b128 v[228:231], v141 offset:39936
	global_load_lds_dwordx4 v[236:237], off
	v_lshl_add_u64 v[236:237], s[38:39], 0, v[130:131]
	s_mov_b32 m0, s29
	s_nop 0
	global_load_lds_dwordx4 v[236:237], off
	s_waitcnt vmcnt(8)
	s_waitcnt lgkmcnt(0)
	s_setprio 1
	s_barrier
	v_mfma_f32_16x16x32_bf16 v[124:127], v[142:145], v[194:197], v[124:127]
	v_mfma_f32_16x16x32_bf16 v[120:123], v[170:173], v[194:197], v[120:123]
	v_mfma_f32_16x16x32_bf16 v[108:111], v[142:145], v[202:205], v[108:111]
	v_mfma_f32_16x16x32_bf16 v[104:107], v[170:173], v[202:205], v[104:107]
	v_mfma_f32_16x16x32_bf16 v[92:95], v[142:145], v[210:213], v[92:95]
	v_mfma_f32_16x16x32_bf16 v[88:91], v[170:173], v[210:213], v[88:91]
	v_mfma_f32_16x16x32_bf16 v[76:79], v[142:145], v[224:227], v[76:79]
	v_mfma_f32_16x16x32_bf16 v[72:75], v[170:173], v[224:227], v[72:75]
	v_mfma_f32_16x16x32_bf16 v[124:127], v[146:149], v[198:201], v[124:127]
	v_mfma_f32_16x16x32_bf16 v[120:123], v[174:177], v[198:201], v[120:123]
	v_mfma_f32_16x16x32_bf16 v[108:111], v[146:149], v[206:209], v[108:111]
	v_mfma_f32_16x16x32_bf16 v[104:107], v[174:177], v[206:209], v[104:107]
	v_mfma_f32_16x16x32_bf16 v[92:95], v[146:149], v[220:223], v[92:95]
	v_mfma_f32_16x16x32_bf16 v[88:91], v[174:177], v[220:223], v[88:91]
	v_mfma_f32_16x16x32_bf16 v[76:79], v[146:149], v[228:231], v[76:79]
	v_mfma_f32_16x16x32_bf16 v[72:75], v[174:177], v[228:231], v[72:75]
	v_mfma_f32_16x16x32_bf16 v[116:119], v[178:181], v[194:197], v[116:119]
	v_mfma_f32_16x16x32_bf16 v[112:115], v[186:189], v[194:197], v[112:115]
	v_mfma_f32_16x16x32_bf16 v[100:103], v[178:181], v[202:205], v[100:103]
	v_mfma_f32_16x16x32_bf16 v[96:99], v[186:189], v[202:205], v[96:99]
	v_mfma_f32_16x16x32_bf16 v[84:87], v[178:181], v[210:213], v[84:87]
	v_mfma_f32_16x16x32_bf16 v[80:83], v[186:189], v[210:213], v[80:83]
	v_mfma_f32_16x16x32_bf16 v[68:71], v[178:181], v[224:227], v[68:71]
	v_mfma_f32_16x16x32_bf16 v[64:67], v[186:189], v[224:227], v[64:67]
	v_mfma_f32_16x16x32_bf16 v[116:119], v[182:185], v[198:201], v[116:119]
	v_mfma_f32_16x16x32_bf16 v[112:115], v[190:193], v[198:201], v[112:115]
	v_mfma_f32_16x16x32_bf16 v[100:103], v[182:185], v[206:209], v[100:103]
	v_mfma_f32_16x16x32_bf16 v[96:99], v[190:193], v[206:209], v[96:99]
	v_mfma_f32_16x16x32_bf16 v[84:87], v[182:185], v[220:223], v[84:87]
	v_mfma_f32_16x16x32_bf16 v[80:83], v[190:193], v[220:223], v[80:83]
	v_mfma_f32_16x16x32_bf16 v[68:71], v[182:185], v[228:231], v[68:71]
	s_setprio 0
	v_mfma_f32_16x16x32_bf16 v[64:67], v[190:193], v[228:231], v[64:67]
	s_barrier
; #define PG8_STAGE(bufoff, gbase, voff) do { _Pragma("unroll") for (int _i = 0; _i < 2; ++_i) \
;         __builtin_amdgcn_global_load_lds((const unsigned*)((const char*)(gbase) + (voff)[_i]), (PG8_LAS unsigned*)(lds + (bufoff) + ldsw + _i * 8192), 16, 0, 0); } while (0)
; #define PG8_LDA(dst, b, h) do { _Pragma("unroll") for (int m = 0; m < 4; ++m) _Pragma("unroll") for (int k = 0; k < 2; ++k) dst[m][k] = *(const PG8_LAS bf16x8*)(lds + PG8_SA(b, h) + aoff + m * 2048 + k * 1024); } while (0)
; #define PG8_MMA(ai, bj, At, Bt) do { __builtin_amdgcn_s_setprio(1); _Pragma("unroll") for (int m = 0; m < 4; ++m) _Pragma("unroll") for (int n = 0; n < 2; ++n) _Pragma("unroll") for (int k = 0; k < 2; ++k) \
;         acc[ai][bj][m][n] = __builtin_amdgcn_mfma_f32_16x16x32_bf16(Bt[n][k], At[m][k], acc[ai][bj][m][n], 0, 0, 0); __builtin_amdgcn_s_setprio(0); } while (0)
; #define PG8_WAIT_V(n) asm volatile("s_waitcnt vmcnt(" #n ")" ::: "memory")
; #define PG8_WAIT_L(n) asm volatile("s_waitcnt lgkmcnt(" #n ")" ::: "memory")
; #define PG8_BAR __builtin_amdgcn_s_barrier()
; #define PG8_SCHED __builtin_amdgcn_sched_barrier(0)
; template <class Epi, class Sched, bool ALIGN_EPI = false, bool SP2 = false>
; __device__ __forceinline__ void gemm_phase(PG8_LAS unsigned char* lds, const Gemm g, const Sched& S, const Epi& E) {
;     ...
;         for (int t = 0; t < nt; t += 2) {
;     ...
;             PG8_LDA(At, 1, 1); PG8_STAGE(PG8_SB(1, 0), b3, voffB); PG8_STAGE(PG8_SB(1, 1), b3 + hstep, voffB); PG8_STAGE(PG8_SA(1, 0), a3, voffA);
;             PG8_WAIT_V(8); PG8_WAIT_L(0); PG8_BAR; PG8_MMA(1, 0, At, B0); PG8_MMA(1, 1, At, B1); PG8_BAR; PG8_SCHED;
	s_add_i32 s38, s44, s26
	v_lshl_add_u64 v[150:151], v[150:151], 0, s[90:91]
	s_mov_b32 m0, s38
	ds_read_b128 v[194:197], v141 offset:49152
	ds_read_b128 v[198:201], v141 offset:50176
	ds_read_b128 v[202:205], v141 offset:51200
	ds_read_b128 v[206:209], v141 offset:52224
	ds_read_b128 v[210:213], v141 offset:53248
	ds_read_b128 v[220:223], v141 offset:54272
	ds_read_b128 v[224:227], v141 offset:55296
	ds_read_b128 v[228:231], v141 offset:56320
	global_load_lds_dwordx4 v[150:151], off
	s_add_i32 m0, s38, 0x2000
	s_add_u32 s18, s18, 0x80080
	v_lshl_add_u64 v[150:151], v[214:215], 0, s[90:91]
	s_addc_u32 s19, s19, 0
	s_add_i32 s38, s45, s26
	global_load_lds_dwordx4 v[150:151], off
	v_lshl_add_u64 v[150:151], s[18:19], 0, v[152:153]
	s_mov_b32 m0, s38
	s_nop 0
	global_load_lds_dwordx4 v[150:151], off
	v_lshl_add_u64 v[150:151], s[18:19], 0, v[128:129]
	s_add_i32 m0, s38, 0x2000
	s_nop 0
	global_load_lds_dwordx4 v[150:151], off
	v_lshl_add_u64 v[150:151], v[232:233], 0, s[90:91]
	s_mov_b32 m0, s33
	s_nop 0
	global_load_lds_dwordx4 v[150:151], off
	v_lshl_add_u64 v[150:151], v[234:235], 0, s[90:91]
	s_mov_b32 m0, s40
	s_nop 0
	global_load_lds_dwordx4 v[150:151], off
	s_waitcnt vmcnt(8)
	s_waitcnt lgkmcnt(0)
	s_setprio 1
	s_barrier
	v_mfma_f32_16x16x32_bf16 v[60:63], v[142:145], v[194:197], v[60:63]
	v_mfma_f32_16x16x32_bf16 v[56:59], v[170:173], v[194:197], v[56:59]
	v_mfma_f32_16x16x32_bf16 v[44:47], v[142:145], v[202:205], v[44:47]
	v_mfma_f32_16x16x32_bf16 v[40:43], v[170:173], v[202:205], v[40:43]
	v_mfma_f32_16x16x32_bf16 v[28:31], v[142:145], v[210:213], v[28:31]
	v_mfma_f32_16x16x32_bf16 v[24:27], v[170:173], v[210:213], v[24:27]
	v_mfma_f32_16x16x32_bf16 v[12:15], v[142:145], v[224:227], v[12:15]
	v_mfma_f32_16x16x32_bf16 v[8:11], v[170:173], v[224:227], v[8:11]
	v_mfma_f32_16x16x32_bf16 v[60:63], v[146:149], v[198:201], v[60:63]
	v_mfma_f32_16x16x32_bf16 v[56:59], v[174:177], v[198:201], v[56:59]
	v_mfma_f32_16x16x32_bf16 v[44:47], v[146:149], v[206:209], v[44:47]
	v_mfma_f32_16x16x32_bf16 v[40:43], v[174:177], v[206:209], v[40:43]
	v_mfma_f32_16x16x32_bf16 v[28:31], v[146:149], v[220:223], v[28:31]
	v_mfma_f32_16x16x32_bf16 v[24:27], v[174:177], v[220:223], v[24:27]
	v_mfma_f32_16x16x32_bf16 v[12:15], v[146:149], v[228:231], v[12:15]
	v_mfma_f32_16x16x32_bf16 v[8:11], v[174:177], v[228:231], v[8:11]
	v_mfma_f32_16x16x32_bf16 v[52:55], v[178:181], v[194:197], v[52:55]
	v_mfma_f32_16x16x32_bf16 v[48:51], v[186:189], v[194:197], v[48:51]
	v_mfma_f32_16x16x32_bf16 v[36:39], v[178:181], v[202:205], v[36:39]
	v_mfma_f32_16x16x32_bf16 v[32:35], v[186:189], v[202:205], v[32:35]
	v_mfma_f32_16x16x32_bf16 v[20:23], v[178:181], v[210:213], v[20:23]
	v_mfma_f32_16x16x32_bf16 v[16:19], v[186:189], v[210:213], v[16:19]
	v_mfma_f32_16x16x32_bf16 v[4:7], v[178:181], v[224:227], v[4:7]
	v_mfma_f32_16x16x32_bf16 v[0:3], v[186:189], v[224:227], v[0:3]
	v_mfma_f32_16x16x32_bf16 v[52:55], v[182:185], v[198:201], v[52:55]
	v_mfma_f32_16x16x32_bf16 v[48:51], v[190:193], v[198:201], v[48:51]
	v_mfma_f32_16x16x32_bf16 v[36:39], v[182:185], v[206:209], v[36:39]
	v_mfma_f32_16x16x32_bf16 v[32:35], v[190:193], v[206:209], v[32:35]
	v_mfma_f32_16x16x32_bf16 v[20:23], v[182:185], v[220:223], v[20:23]
	v_mfma_f32_16x16x32_bf16 v[16:19], v[190:193], v[220:223], v[16:19]
	v_mfma_f32_16x16x32_bf16 v[4:7], v[182:185], v[228:231], v[4:7]
	s_setprio 0
	v_mfma_f32_16x16x32_bf16 v[0:3], v[190:193], v[228:231], v[0:3]
	s_barrier
	s_add_i32 s43, s43, 2
	s_add_u32 s16, s16, 0x100
	s_addc_u32 s17, s17, 0
	s_cmp_gt_u32 s43, 29
	s_cbranch_scc0 .LBB0_291
	s_cmpk_lt_u32 s25, 0x100
	s_cbranch_scc0 .LBB0_294
	s_barrier

; #define PG8_STAGE(bufoff, gbase, voff) do { _Pragma("unroll") for (int _i = 0; _i < 2; ++_i) \
;         __builtin_amdgcn_global_load_lds((const unsigned*)((const char*)(gbase) + (voff)[_i]), (PG8_LAS unsigned*)(lds + (bufoff) + ldsw + _i * 8192), 16, 0, 0); } while (0)
; #define PG8_LDA(dst, b, h) do { _Pragma("unroll") for (int m = 0; m < 4; ++m) _Pragma("unroll") for (int k = 0; k < 2; ++k) dst[m][k] = *(const PG8_LAS bf16x8*)(lds + PG8_SA(b, h) + aoff + m * 2048 + k * 1024); } while (0)
; #define PG8_LDB(dst, b, h) do { _Pragma("unroll") for (int n = 0; n < 2; ++n) _Pragma("unroll") for (int k = 0; k < 2; ++k) dst[n][k] = *(const PG8_LAS bf16x8*)(lds + PG8_SB(b, h) + boff + n * 2048 + k * 1024); } while (0)
; #define PG8_MMA(ai, bj, At, Bt) do { __builtin_amdgcn_s_setprio(1); _Pragma("unroll") for (int m = 0; m < 4; ++m) _Pragma("unroll") for (int n = 0; n < 2; ++n) _Pragma("unroll") for (int k = 0; k < 2; ++k) \
;         acc[ai][bj][m][n] = __builtin_amdgcn_mfma_f32_16x16x32_bf16(Bt[n][k], At[m][k], acc[ai][bj][m][n], 0, 0, 0); __builtin_amdgcn_s_setprio(0); } while (0)
; #define PG8_BAR __builtin_amdgcn_s_barrier()
; template <class Epi, class Sched, bool ALIGN_EPI = false, bool SP2 = false>
; __device__ __forceinline__ void gemm_phase(PG8_LAS unsigned char* lds, const Gemm g, const Sched& S, const Epi& E) {
;     ...
;         const bool has_next = S.next(ui + 1, nxt);
;         const char* nA = has_next ? (const char*)g.A + (size_t)nxt.pm * tstep : cA; const char* nB = has_next ? (const char*)g.Bt + (size_t)nxt.pn * tstep : cB;
;         for (int t = 0; t < nt; t += 2) {
;             const bool last = (t == nt - 2);
;             const char* a1 = cA + (size_t)(t + 1) * kstep;
;             const char* a2 = last ? nA : cA + (size_t)(t + 2) * kstep; const char* b2 = last ? nB : cB + (size_t)(t + 2) * kstep;
;             const char* a3 = a2 + kstep; const char* b3 = b2 + kstep;
;             if (last && has_next) S.a_ready(nxt);
;             if constexpr (SP2) {
;             PG8_LDB(B0, 0, 0); PG8_LDB(B1, 0, 1); PG8_SCHED; PG8_LDA(At, 0, 0); PG8_STAGE(PG8_SA(1, 1), a1 + hstep, voffA);
;             PG8_WAIT_V(8); PG8_WAIT_L(0); PG8_BAR; PG8_MMA(0, 0, At, B0); PG8_MMA(0, 1, At, B1); PG8_BAR; PG8_SCHED;
;             PG8_LDA(At, 0, 1); PG8_STAGE(PG8_SB(0, 0), b2, voffB); PG8_STAGE(PG8_SB(0, 1), b2 + hstep, voffB); PG8_STAGE(PG8_SA(0, 0), a2, voffA);
.LBB0_349:
	s_or_b32 s4, s48, 1
	s_add_i32 s48, s48, 2
	s_mov_b32 s49, s5
	s_lshl_b64 s[58:59], s[4:5], 7
	s_lshl_b64 s[82:83], s[48:49], 7
	s_add_u32 s4, s14, s82
	s_addc_u32 s33, s15, s83
	s_and_b64 s[56:57], s[54:55], exec
	s_cselect_b32 s57, s45, s33
	s_cselect_b32 s56, s44, s4
	s_add_u32 s4, s16, s82
	s_addc_u32 s33, s17, s83
	s_and_b64 s[54:55], s[54:55], exec
	s_cselect_b32 s55, s47, s33
	s_cselect_b32 s54, s46, s4
	s_add_i32 s4, 0, 0x10000
	v_add_u32_e32 v150, s4, v135
	s_add_i32 s33, 0, 0x14000
	ds_read_b128 v[138:141], v150
	ds_read_b128 v[142:145], v150 offset:1024
	ds_read_b128 v[146:149], v150 offset:2048
	ds_read_b128 v[170:173], v150 offset:3072
	v_add_u32_e32 v150, s33, v135
	ds_read_b128 v[174:177], v150
	ds_read_b128 v[178:181], v150 offset:1024
	ds_read_b128 v[182:185], v150 offset:2048
	ds_read_b128 v[186:189], v150 offset:3072
	s_add_u32 s58, s25, s58
	s_addc_u32 s59, s29, s59
	v_lshl_add_u64 v[150:151], s[58:59], 0, v[128:129]
	s_add_i32 m0, s69, 0xc000
	ds_read_b128 v[190:193], v137
	ds_read_b128 v[194:197], v137 offset:1024
	ds_read_b128 v[198:201], v137 offset:2048
	ds_read_b128 v[202:205], v137 offset:3072
	ds_read_b128 v[206:209], v137 offset:4096
	ds_read_b128 v[210:213], v137 offset:5120
	ds_read_b128 v[220:223], v137 offset:6144
	ds_read_b128 v[224:227], v137 offset:7168
	global_load_lds_dwordx4 v[150:151], off
	v_lshl_add_u64 v[150:151], s[58:59], 0, v[130:131]
	s_add_i32 m0, s69, 0xe000
	s_nop 0
	global_load_lds_dwordx4 v[150:151], off
	s_waitcnt vmcnt(8)
	s_waitcnt lgkmcnt(0)
	s_setprio 1
	s_barrier
	v_mfma_f32_16x16x32_bf16 v[124:127], v[138:141], v[190:193], v[124:127]
	v_mfma_f32_16x16x32_bf16 v[120:123], v[146:149], v[190:193], v[120:123]
	v_mfma_f32_16x16x32_bf16 v[116:119], v[138:141], v[198:201], v[116:119]
	v_mfma_f32_16x16x32_bf16 v[112:115], v[146:149], v[198:201], v[112:115]
	v_mfma_f32_16x16x32_bf16 v[108:111], v[138:141], v[206:209], v[108:111]
	v_mfma_f32_16x16x32_bf16 v[104:107], v[146:149], v[206:209], v[104:107]
	v_mfma_f32_16x16x32_bf16 v[100:103], v[138:141], v[220:223], v[100:103]
	v_mfma_f32_16x16x32_bf16 v[96:99], v[146:149], v[220:223], v[96:99]
	v_mfma_f32_16x16x32_bf16 v[124:127], v[142:145], v[194:197], v[124:127]
	v_mfma_f32_16x16x32_bf16 v[120:123], v[170:173], v[194:197], v[120:123]
	v_mfma_f32_16x16x32_bf16 v[116:119], v[142:145], v[202:205], v[116:119]
	v_mfma_f32_16x16x32_bf16 v[112:115], v[170:173], v[202:205], v[112:115]
	v_mfma_f32_16x16x32_bf16 v[108:111], v[142:145], v[210:213], v[108:111]
	v_mfma_f32_16x16x32_bf16 v[104:107], v[170:173], v[210:213], v[104:107]
	v_mfma_f32_16x16x32_bf16 v[100:103], v[142:145], v[224:227], v[100:103]
	v_mfma_f32_16x16x32_bf16 v[96:99], v[170:173], v[224:227], v[96:99]
	v_mfma_f32_16x16x32_bf16 v[92:95], v[174:177], v[190:193], v[92:95]
	v_mfma_f32_16x16x32_bf16 v[88:91], v[182:185], v[190:193], v[88:91]
	v_mfma_f32_16x16x32_bf16 v[84:87], v[174:177], v[198:201], v[84:87]
	v_mfma_f32_16x16x32_bf16 v[80:83], v[182:185], v[198:201], v[80:83]
	v_mfma_f32_16x16x32_bf16 v[76:79], v[174:177], v[206:209], v[76:79]
	v_mfma_f32_16x16x32_bf16 v[72:75], v[182:185], v[206:209], v[72:75]
	v_mfma_f32_16x16x32_bf16 v[68:71], v[174:177], v[220:223], v[68:71]
	v_mfma_f32_16x16x32_bf16 v[64:67], v[182:185], v[220:223], v[64:67]
	v_mfma_f32_16x16x32_bf16 v[92:95], v[178:181], v[194:197], v[92:95]
	v_mfma_f32_16x16x32_bf16 v[88:91], v[186:189], v[194:197], v[88:91]
	v_mfma_f32_16x16x32_bf16 v[84:87], v[178:181], v[202:205], v[84:87]
	v_mfma_f32_16x16x32_bf16 v[80:83], v[186:189], v[202:205], v[80:83]
	v_mfma_f32_16x16x32_bf16 v[76:79], v[178:181], v[210:213], v[76:79]
	v_mfma_f32_16x16x32_bf16 v[72:75], v[186:189], v[210:213], v[72:75]
	v_mfma_f32_16x16x32_bf16 v[68:71], v[178:181], v[224:227], v[68:71]
	s_setprio 0
	v_mfma_f32_16x16x32_bf16 v[64:67], v[186:189], v[224:227], v[64:67]
	s_barrier
	s_add_i32 s4, s4, s68
	v_lshl_add_u64 v[150:151], s[54:55], 0, v[152:153]
	s_mov_b32 m0, s4
	ds_read_b128 v[190:193], v137 offset:16384
	ds_read_b128 v[194:197], v137 offset:17408
	ds_read_b128 v[198:201], v137 offset:18432
	ds_read_b128 v[202:205], v137 offset:19456
	ds_read_b128 v[206:209], v137 offset:20480
	ds_read_b128 v[210:213], v137 offset:21504
	ds_read_b128 v[220:223], v137 offset:22528
	ds_read_b128 v[224:227], v137 offset:23552
	global_load_lds_dwordx4 v[150:151], off
	s_add_i32 m0, s4, 0x2000
	v_lshl_add_u64 v[214:215], s[54:55], 0, v[132:133]
	s_add_u32 s54, s54, s66
	s_addc_u32 s55, s55, 0
	s_add_i32 s4, s33, s68
	global_load_lds_dwordx4 v[214:215], off
	v_lshl_add_u64 v[228:229], s[54:55], 0, v[152:153]
	s_mov_b32 m0, s4
	v_lshl_add_u64 v[230:231], s[54:55], 0, v[132:133]
	global_load_lds_dwordx4 v[228:229], off
	s_add_i32 m0, s4, 0x2000
	v_lshl_add_u64 v[232:233], s[56:57], 0, v[128:129]
	global_load_lds_dwordx4 v[230:231], off
	s_mov_b32 m0, s69
	v_lshl_add_u64 v[234:235], s[56:57], 0, v[130:131]
	global_load_lds_dwordx4 v[232:233], off
	s_mov_b32 m0, s70
	s_nop 0
	global_load_lds_dwordx4 v[234:235], off
	s_waitcnt vmcnt(8)
	s_waitcnt lgkmcnt(0)
	s_setprio 1
	s_barrier
; #define PG8_STAGE(bufoff, gbase, voff) do { _Pragma("unroll") for (int _i = 0; _i < 2; ++_i) \
;         __builtin_amdgcn_global_load_lds((const unsigned*)((const char*)(gbase) + (voff)[_i]), (PG8_LAS unsigned*)(lds + (bufoff) + ldsw + _i * 8192), 16, 0, 0); } while (0)
; #define PG8_LDA(dst, b, h) do { _Pragma("unroll") for (int m = 0; m < 4; ++m) _Pragma("unroll") for (int k = 0; k < 2; ++k) dst[m][k] = *(const PG8_LAS bf16x8*)(lds + PG8_SA(b, h) + aoff + m * 2048 + k * 1024); } while (0)
; #define PG8_LDB(dst, b, h) do { _Pragma("unroll") for (int n = 0; n < 2; ++n) _Pragma("unroll") for (int k = 0; k < 2; ++k) dst[n][k] = *(const PG8_LAS bf16x8*)(lds + PG8_SB(b, h) + boff + n * 2048 + k * 1024); } while (0)
; #define PG8_MMA(ai, bj, At, Bt) do { __builtin_amdgcn_s_setprio(1); _Pragma("unroll") for (int m = 0; m < 4; ++m) _Pragma("unroll") for (int n = 0; n < 2; ++n) _Pragma("unroll") for (int k = 0; k < 2; ++k) \
;         acc[ai][bj][m][n] = __builtin_amdgcn_mfma_f32_16x16x32_bf16(Bt[n][k], At[m][k], acc[ai][bj][m][n], 0, 0, 0); __builtin_amdgcn_s_setprio(0); } while (0)
; #define PG8_WAIT_V(n) asm volatile("s_waitcnt vmcnt(" #n ")" ::: "memory")
; #define PG8_WAIT_L(n) asm volatile("s_waitcnt lgkmcnt(" #n ")" ::: "memory")
; #define PG8_BAR __builtin_amdgcn_s_barrier()
; #define PG8_SCHED __builtin_amdgcn_sched_barrier(0)
; template <class Epi, class Sched, bool ALIGN_EPI = false, bool SP2 = false>
; __device__ __forceinline__ void gemm_phase(PG8_LAS unsigned char* lds, const Gemm g, const Sched& S, const Epi& E) {
;     ...
;             PG8_WAIT_V(8); PG8_WAIT_L(0); PG8_BAR; PG8_MMA(1, 0, At, B0); PG8_MMA(1, 1, At, B1); PG8_BAR; PG8_SCHED;
;             PG8_LDB(B0, 1, 0); PG8_LDB(B1, 1, 1); PG8_SCHED; PG8_LDA(At, 1, 0); PG8_STAGE(PG8_SA(0, 1), a2 + hstep, voffA);
;             PG8_WAIT_V(8); PG8_WAIT_L(0); PG8_BAR; PG8_MMA(0, 0, At, B0); PG8_MMA(0, 1, At, B1); PG8_BAR; PG8_SCHED;
	v_mfma_f32_16x16x32_bf16 v[60:63], v[138:141], v[190:193], v[60:63]
	v_mfma_f32_16x16x32_bf16 v[56:59], v[146:149], v[190:193], v[56:59]
	v_mfma_f32_16x16x32_bf16 v[52:55], v[138:141], v[198:201], v[52:55]
	v_mfma_f32_16x16x32_bf16 v[48:51], v[146:149], v[198:201], v[48:51]
	v_mfma_f32_16x16x32_bf16 v[44:47], v[138:141], v[206:209], v[44:47]
	v_mfma_f32_16x16x32_bf16 v[40:43], v[146:149], v[206:209], v[40:43]
	v_mfma_f32_16x16x32_bf16 v[36:39], v[138:141], v[220:223], v[36:39]
	v_mfma_f32_16x16x32_bf16 v[32:35], v[146:149], v[220:223], v[32:35]
	v_mfma_f32_16x16x32_bf16 v[60:63], v[142:145], v[194:197], v[60:63]
	v_mfma_f32_16x16x32_bf16 v[56:59], v[170:173], v[194:197], v[56:59]
	v_mfma_f32_16x16x32_bf16 v[52:55], v[142:145], v[202:205], v[52:55]
	v_mfma_f32_16x16x32_bf16 v[48:51], v[170:173], v[202:205], v[48:51]
	v_mfma_f32_16x16x32_bf16 v[44:47], v[142:145], v[210:213], v[44:47]
	v_mfma_f32_16x16x32_bf16 v[40:43], v[170:173], v[210:213], v[40:43]
	v_mfma_f32_16x16x32_bf16 v[36:39], v[142:145], v[224:227], v[36:39]
	v_mfma_f32_16x16x32_bf16 v[32:35], v[170:173], v[224:227], v[32:35]
	v_mfma_f32_16x16x32_bf16 v[28:31], v[174:177], v[190:193], v[28:31]
	v_mfma_f32_16x16x32_bf16 v[24:27], v[182:185], v[190:193], v[24:27]
	v_mfma_f32_16x16x32_bf16 v[20:23], v[174:177], v[198:201], v[20:23]
	v_mfma_f32_16x16x32_bf16 v[16:19], v[182:185], v[198:201], v[16:19]
	v_mfma_f32_16x16x32_bf16 v[12:15], v[174:177], v[206:209], v[12:15]
	v_mfma_f32_16x16x32_bf16 v[8:11], v[182:185], v[206:209], v[8:11]
	v_mfma_f32_16x16x32_bf16 v[4:7], v[174:177], v[220:223], v[4:7]
	v_mfma_f32_16x16x32_bf16 v[0:3], v[182:185], v[220:223], v[0:3]
	v_mfma_f32_16x16x32_bf16 v[28:31], v[178:181], v[194:197], v[28:31]
	v_mfma_f32_16x16x32_bf16 v[24:27], v[186:189], v[194:197], v[24:27]
	v_mfma_f32_16x16x32_bf16 v[20:23], v[178:181], v[202:205], v[20:23]
	v_mfma_f32_16x16x32_bf16 v[16:19], v[186:189], v[202:205], v[16:19]
	v_mfma_f32_16x16x32_bf16 v[12:15], v[178:181], v[210:213], v[12:15]
	v_mfma_f32_16x16x32_bf16 v[8:11], v[186:189], v[210:213], v[8:11]
	v_mfma_f32_16x16x32_bf16 v[4:7], v[178:181], v[224:227], v[4:7]
	s_setprio 0
	v_mfma_f32_16x16x32_bf16 v[0:3], v[186:189], v[224:227], v[0:3]
	s_barrier
	s_add_i32 s4, 0, 0x18000
	s_add_i32 s33, 0, 0x1c000
	v_add_u32_e32 v170, s4, v135
	v_add_u32_e32 v186, s33, v135
	ds_read_b128 v[138:141], v170
	ds_read_b128 v[142:145], v170 offset:1024
	ds_read_b128 v[146:149], v170 offset:2048
	ds_read_b128 v[170:173], v170 offset:3072
	ds_read_b128 v[174:177], v186
	ds_read_b128 v[178:181], v186 offset:1024
	ds_read_b128 v[182:185], v186 offset:2048
	ds_read_b128 v[186:189], v186 offset:3072
	s_add_u32 s54, s56, s66
	s_addc_u32 s55, s57, 0
	s_mov_b32 m0, s71
	v_lshl_add_u64 v[236:237], s[54:55], 0, v[128:129]
	ds_read_b128 v[190:193], v137 offset:32768
	ds_read_b128 v[194:197], v137 offset:33792
	ds_read_b128 v[198:201], v137 offset:34816
	ds_read_b128 v[202:205], v137 offset:35840
	ds_read_b128 v[206:209], v137 offset:36864
	ds_read_b128 v[210:213], v137 offset:37888
	ds_read_b128 v[220:223], v137 offset:38912
	ds_read_b128 v[224:227], v137 offset:39936
	global_load_lds_dwordx4 v[236:237], off
	v_lshl_add_u64 v[236:237], s[54:55], 0, v[130:131]
	s_mov_b32 m0, s72
	s_nop 0
	global_load_lds_dwordx4 v[236:237], off
	s_waitcnt vmcnt(8)
	s_waitcnt lgkmcnt(0)
	s_setprio 1
	s_barrier
	v_mfma_f32_16x16x32_bf16 v[124:127], v[138:141], v[190:193], v[124:127]
	v_mfma_f32_16x16x32_bf16 v[120:123], v[146:149], v[190:193], v[120:123]
	v_mfma_f32_16x16x32_bf16 v[116:119], v[138:141], v[198:201], v[116:119]
	v_mfma_f32_16x16x32_bf16 v[112:115], v[146:149], v[198:201], v[112:115]
	v_mfma_f32_16x16x32_bf16 v[108:111], v[138:141], v[206:209], v[108:111]
	v_mfma_f32_16x16x32_bf16 v[104:107], v[146:149], v[206:209], v[104:107]
	v_mfma_f32_16x16x32_bf16 v[100:103], v[138:141], v[220:223], v[100:103]
	v_mfma_f32_16x16x32_bf16 v[96:99], v[146:149], v[220:223], v[96:99]
	v_mfma_f32_16x16x32_bf16 v[124:127], v[142:145], v[194:197], v[124:127]
	v_mfma_f32_16x16x32_bf16 v[120:123], v[170:173], v[194:197], v[120:123]
	v_mfma_f32_16x16x32_bf16 v[116:119], v[142:145], v[202:205], v[116:119]
	v_mfma_f32_16x16x32_bf16 v[112:115], v[170:173], v[202:205], v[112:115]
	v_mfma_f32_16x16x32_bf16 v[108:111], v[142:145], v[210:213], v[108:111]
	v_mfma_f32_16x16x32_bf16 v[104:107], v[170:173], v[210:213], v[104:107]
	v_mfma_f32_16x16x32_bf16 v[100:103], v[142:145], v[224:227], v[100:103]
	v_mfma_f32_16x16x32_bf16 v[96:99], v[170:173], v[224:227], v[96:99]
	v_mfma_f32_16x16x32_bf16 v[92:95], v[174:177], v[190:193], v[92:95]
	v_mfma_f32_16x16x32_bf16 v[88:91], v[182:185], v[190:193], v[88:91]
	v_mfma_f32_16x16x32_bf16 v[84:87], v[174:177], v[198:201], v[84:87]
	v_mfma_f32_16x16x32_bf16 v[80:83], v[182:185], v[198:201], v[80:83]
	v_mfma_f32_16x16x32_bf16 v[76:79], v[174:177], v[206:209], v[76:79]
	v_mfma_f32_16x16x32_bf16 v[72:75], v[182:185], v[206:209], v[72:75]
	v_mfma_f32_16x16x32_bf16 v[68:71], v[174:177], v[220:223], v[68:71]
	v_mfma_f32_16x16x32_bf16 v[64:67], v[182:185], v[220:223], v[64:67]
	v_mfma_f32_16x16x32_bf16 v[92:95], v[178:181], v[194:197], v[92:95]
	v_mfma_f32_16x16x32_bf16 v[88:91], v[186:189], v[194:197], v[88:91]
	v_mfma_f32_16x16x32_bf16 v[84:87], v[178:181], v[202:205], v[84:87]
	v_mfma_f32_16x16x32_bf16 v[80:83], v[186:189], v[202:205], v[80:83]
	v_mfma_f32_16x16x32_bf16 v[76:79], v[178:181], v[210:213], v[76:79]
	v_mfma_f32_16x16x32_bf16 v[72:75], v[186:189], v[210:213], v[72:75]
	v_mfma_f32_16x16x32_bf16 v[68:71], v[178:181], v[224:227], v[68:71]
	s_setprio 0
	v_mfma_f32_16x16x32_bf16 v[64:67], v[186:189], v[224:227], v[64:67]
	s_barrier
; #define PG8_STAGE(bufoff, gbase, voff) do { _Pragma("unroll") for (int _i = 0; _i < 2; ++_i) \
;         __builtin_amdgcn_global_load_lds((const unsigned*)((const char*)(gbase) + (voff)[_i]), (PG8_LAS unsigned*)(lds + (bufoff) + ldsw + _i * 8192), 16, 0, 0); } while (0)
; #define PG8_LDA(dst, b, h) do { _Pragma("unroll") for (int m = 0; m < 4; ++m) _Pragma("unroll") for (int k = 0; k < 2; ++k) dst[m][k] = *(const PG8_LAS bf16x8*)(lds + PG8_SA(b, h) + aoff + m * 2048 + k * 1024); } while (0)
; #define PG8_MMA(ai, bj, At, Bt) do { __builtin_amdgcn_s_setprio(1); _Pragma("unroll") for (int m = 0; m < 4; ++m) _Pragma("unroll") for (int n = 0; n < 2; ++n) _Pragma("unroll") for (int k = 0; k < 2; ++k) \
;         acc[ai][bj][m][n] = __builtin_amdgcn_mfma_f32_16x16x32_bf16(Bt[n][k], At[m][k], acc[ai][bj][m][n], 0, 0, 0); __builtin_amdgcn_s_setprio(0); } while (0)
; #define PG8_WAIT_V(n) asm volatile("s_waitcnt vmcnt(" #n ")" ::: "memory")
; #define PG8_WAIT_L(n) asm volatile("s_waitcnt lgkmcnt(" #n ")" ::: "memory")
; #define PG8_BAR __builtin_amdgcn_s_barrier()
; #define PG8_SCHED __builtin_amdgcn_sched_barrier(0)
; template <class Epi, class Sched, bool ALIGN_EPI = false, bool SP2 = false>
; __device__ __forceinline__ void gemm_phase(PG8_LAS unsigned char* lds, const Gemm g, const Sched& S, const Epi& E) {
;     ...
;         for (int t = 0; t < nt; t += 2) {
;     ...
;             PG8_LDA(At, 1, 1); PG8_STAGE(PG8_SB(1, 0), b3, voffB); PG8_STAGE(PG8_SB(1, 1), b3 + hstep, voffB); PG8_STAGE(PG8_SA(1, 0), a3, voffA);
;             PG8_WAIT_V(8); PG8_WAIT_L(0); PG8_BAR; PG8_MMA(1, 0, At, B0); PG8_MMA(1, 1, At, B1); PG8_BAR; PG8_SCHED;
	s_add_i32 s4, s4, s68
	v_lshl_add_u64 v[150:151], v[150:151], 0, s[90:91]
	s_mov_b32 m0, s4
	ds_read_b128 v[190:193], v137 offset:49152
	ds_read_b128 v[194:197], v137 offset:50176
	ds_read_b128 v[198:201], v137 offset:51200
	ds_read_b128 v[202:205], v137 offset:52224
	ds_read_b128 v[206:209], v137 offset:53248
	ds_read_b128 v[210:213], v137 offset:54272
	ds_read_b128 v[220:223], v137 offset:55296
	ds_read_b128 v[224:227], v137 offset:56320
	global_load_lds_dwordx4 v[150:151], off
	v_lshl_add_u64 v[150:151], v[214:215], 0, s[90:91]
	s_add_i32 m0, s4, 0x2000
	s_add_i32 s4, s33, s68
	global_load_lds_dwordx4 v[150:151], off
	v_lshl_add_u64 v[150:151], v[228:229], 0, s[90:91]
	s_mov_b32 m0, s4
	s_nop 0
	global_load_lds_dwordx4 v[150:151], off
	v_lshl_add_u64 v[150:151], v[230:231], 0, s[90:91]
	s_add_i32 m0, s4, 0x2000
	s_nop 0
	global_load_lds_dwordx4 v[150:151], off
	v_lshl_add_u64 v[150:151], v[232:233], 0, s[90:91]
	s_mov_b32 m0, s75
	s_nop 0
	global_load_lds_dwordx4 v[150:151], off
	v_lshl_add_u64 v[150:151], v[234:235], 0, s[90:91]
	s_mov_b32 m0, s76
	s_nop 0
	global_load_lds_dwordx4 v[150:151], off
	s_waitcnt vmcnt(8)
	s_waitcnt lgkmcnt(0)
	s_setprio 1
	s_barrier
	v_mfma_f32_16x16x32_bf16 v[60:63], v[138:141], v[190:193], v[60:63]
	v_mfma_f32_16x16x32_bf16 v[56:59], v[146:149], v[190:193], v[56:59]
	v_mfma_f32_16x16x32_bf16 v[52:55], v[138:141], v[198:201], v[52:55]
	v_mfma_f32_16x16x32_bf16 v[48:51], v[146:149], v[198:201], v[48:51]
	v_mfma_f32_16x16x32_bf16 v[44:47], v[138:141], v[206:209], v[44:47]
	v_mfma_f32_16x16x32_bf16 v[40:43], v[146:149], v[206:209], v[40:43]
	v_mfma_f32_16x16x32_bf16 v[36:39], v[138:141], v[220:223], v[36:39]
	v_mfma_f32_16x16x32_bf16 v[32:35], v[146:149], v[220:223], v[32:35]
	v_mfma_f32_16x16x32_bf16 v[60:63], v[142:145], v[194:197], v[60:63]
	v_mfma_f32_16x16x32_bf16 v[56:59], v[170:173], v[194:197], v[56:59]
	v_mfma_f32_16x16x32_bf16 v[52:55], v[142:145], v[202:205], v[52:55]
	v_mfma_f32_16x16x32_bf16 v[48:51], v[170:173], v[202:205], v[48:51]
	v_mfma_f32_16x16x32_bf16 v[44:47], v[142:145], v[210:213], v[44:47]
	v_mfma_f32_16x16x32_bf16 v[40:43], v[170:173], v[210:213], v[40:43]
	v_mfma_f32_16x16x32_bf16 v[36:39], v[142:145], v[224:227], v[36:39]
	v_mfma_f32_16x16x32_bf16 v[32:35], v[170:173], v[224:227], v[32:35]
	v_mfma_f32_16x16x32_bf16 v[28:31], v[174:177], v[190:193], v[28:31]
	v_mfma_f32_16x16x32_bf16 v[24:27], v[182:185], v[190:193], v[24:27]
	v_mfma_f32_16x16x32_bf16 v[20:23], v[174:177], v[198:201], v[20:23]
	v_mfma_f32_16x16x32_bf16 v[16:19], v[182:185], v[198:201], v[16:19]
	v_mfma_f32_16x16x32_bf16 v[12:15], v[174:177], v[206:209], v[12:15]
	v_mfma_f32_16x16x32_bf16 v[8:11], v[182:185], v[206:209], v[8:11]
	v_mfma_f32_16x16x32_bf16 v[4:7], v[174:177], v[220:223], v[4:7]
	v_mfma_f32_16x16x32_bf16 v[0:3], v[182:185], v[220:223], v[0:3]
	v_mfma_f32_16x16x32_bf16 v[28:31], v[178:181], v[194:197], v[28:31]
	v_mfma_f32_16x16x32_bf16 v[24:27], v[186:189], v[194:197], v[24:27]
	v_mfma_f32_16x16x32_bf16 v[20:23], v[178:181], v[202:205], v[20:23]
	v_mfma_f32_16x16x32_bf16 v[16:19], v[186:189], v[202:205], v[16:19]
	v_mfma_f32_16x16x32_bf16 v[12:15], v[178:181], v[210:213], v[12:15]
	v_mfma_f32_16x16x32_bf16 v[8:11], v[186:189], v[210:213], v[8:11]
	v_mfma_f32_16x16x32_bf16 v[4:7], v[178:181], v[224:227], v[4:7]
	s_setprio 0
	v_mfma_f32_16x16x32_bf16 v[0:3], v[186:189], v[224:227], v[0:3]
	s_barrier
	s_cmp_ge_u32 s48, s73
	s_cbranch_scc1 .LBB0_356

; #define PG8_STAGE(bufoff, gbase, voff) do { _Pragma("unroll") for (int _i = 0; _i < 2; ++_i) \
;         __builtin_amdgcn_global_load_lds((const unsigned*)((const char*)(gbase) + (voff)[_i]), (PG8_LAS unsigned*)(lds + (bufoff) + ldsw + _i * 8192), 16, 0, 0); } while (0)
; #define PG8_LDA(dst, b, h) do { _Pragma("unroll") for (int m = 0; m < 4; ++m) _Pragma("unroll") for (int k = 0; k < 2; ++k) dst[m][k] = *(const PG8_LAS bf16x8*)(lds + PG8_SA(b, h) + aoff + m * 2048 + k * 1024); } while (0)
; #define PG8_LDB(dst, b, h) do { _Pragma("unroll") for (int n = 0; n < 2; ++n) _Pragma("unroll") for (int k = 0; k < 2; ++k) dst[n][k] = *(const PG8_LAS bf16x8*)(lds + PG8_SB(b, h) + boff + n * 2048 + k * 1024); } while (0)
; #define PG8_MMA(ai, bj, At, Bt) do { __builtin_amdgcn_s_setprio(1); _Pragma("unroll") for (int m = 0; m < 4; ++m) _Pragma("unroll") for (int n = 0; n < 2; ++n) _Pragma("unroll") for (int k = 0; k < 2; ++k) \
;         acc[ai][bj][m][n] = __builtin_amdgcn_mfma_f32_16x16x32_bf16(Bt[n][k], At[m][k], acc[ai][bj][m][n], 0, 0, 0); __builtin_amdgcn_s_setprio(0); } while (0)
; #define PG8_BAR __builtin_amdgcn_s_barrier()
; template <class Epi, class Sched, bool ALIGN_EPI = false, bool SP2 = false>
; __device__ __forceinline__ void gemm_phase(PG8_LAS unsigned char* lds, const Gemm g, const Sched& S, const Epi& E) {
;     ...
;         const bool has_next = S.next(ui + 1, nxt);
;         const char* nA = has_next ? (const char*)g.A + (size_t)nxt.pm * tstep : cA; const char* nB = has_next ? (const char*)g.Bt + (size_t)nxt.pn * tstep : cB;
;         for (int t = 0; t < nt; t += 2) {
;             const bool last = (t == nt - 2);
;             const char* a1 = cA + (size_t)(t + 1) * kstep;
;             const char* a2 = last ? nA : cA + (size_t)(t + 2) * kstep; const char* b2 = last ? nB : cB + (size_t)(t + 2) * kstep;
;             const char* a3 = a2 + kstep; const char* b3 = b2 + kstep;
;             if (last && has_next) S.a_ready(nxt);
;             if constexpr (SP2) {
;             PG8_LDB(B0, 0, 0); PG8_LDB(B1, 0, 1); PG8_SCHED; PG8_LDA(At, 0, 0); PG8_STAGE(PG8_SA(1, 1), a1 + hstep, voffA);
;             PG8_WAIT_V(8); PG8_WAIT_L(0); PG8_BAR; PG8_MMA(0, 0, At, B0); PG8_MMA(0, 1, At, B1); PG8_BAR; PG8_SCHED;
;             PG8_LDA(At, 0, 1); PG8_STAGE(PG8_SB(0, 0), b2, voffB); PG8_STAGE(PG8_SB(0, 1), b2 + hstep, voffB); PG8_STAGE(PG8_SA(0, 0), a2, voffA);
.LBB0_431:
	s_add_u32 s54, s42, s52
	s_addc_u32 s55, s43, s53
	s_add_u32 s54, s54, 0x100
	s_addc_u32 s55, s55, 0
	s_add_u32 s75, s29, s52
	s_addc_u32 s76, s33, s53
	s_cmpk_eq_i32 s52, 0xf00
	s_cselect_b32 s57, s25, s55
	s_cselect_b32 s56, s47, s54
	s_cselect_b32 s55, s45, s76
	s_cselect_b32 s54, s73, s75
	s_add_i32 s75, 0, 0x10000
	v_add_u32_e32 v152, s75, v145
	s_add_i32 s78, 0, 0x14000
	ds_read_b128 v[148:151], v152
	ds_read_b128 v[170:173], v152 offset:1024
	ds_read_b128 v[174:177], v152 offset:2048
	ds_read_b128 v[178:181], v152 offset:3072
	v_add_u32_e32 v152, s78, v145
	ds_read_b128 v[182:185], v152
	ds_read_b128 v[186:189], v152 offset:1024
	ds_read_b128 v[190:193], v152 offset:2048
	ds_read_b128 v[194:197], v152 offset:3072
	s_add_u32 s76, s42, s52
	s_addc_u32 s77, s43, s53
	s_add_u32 s76, s76, 0x80080
	s_addc_u32 s77, s77, 0
	s_add_i32 m0, s15, 0xc000
	ds_read_b128 v[198:201], v147
	ds_read_b128 v[202:205], v147 offset:1024
	ds_read_b128 v[206:209], v147 offset:2048
	ds_read_b128 v[210:213], v147 offset:3072
	ds_read_b128 v[220:223], v147 offset:4096
	ds_read_b128 v[224:227], v147 offset:5120
	ds_read_b128 v[228:231], v147 offset:6144
	ds_read_b128 v[232:235], v147 offset:7168
	global_load_lds_dwordx4 v136, s[76:77]
	s_add_i32 m0, s15, 0xe000
	s_nop 0
	global_load_lds_dwordx4 v138, s[76:77]
	s_waitcnt vmcnt(8)
	s_waitcnt lgkmcnt(0)
	s_setprio 1
	s_barrier
	v_mfma_f32_16x16x32_bf16 v[124:127], v[148:151], v[198:201], v[124:127]
	v_mfma_f32_16x16x32_bf16 v[120:123], v[174:177], v[198:201], v[120:123]
	v_mfma_f32_16x16x32_bf16 v[116:119], v[148:151], v[206:209], v[116:119]
	v_mfma_f32_16x16x32_bf16 v[112:115], v[174:177], v[206:209], v[112:115]
	v_mfma_f32_16x16x32_bf16 v[108:111], v[148:151], v[220:223], v[108:111]
	v_mfma_f32_16x16x32_bf16 v[104:107], v[174:177], v[220:223], v[104:107]
	v_mfma_f32_16x16x32_bf16 v[100:103], v[148:151], v[228:231], v[100:103]
	v_mfma_f32_16x16x32_bf16 v[96:99], v[174:177], v[228:231], v[96:99]
	v_mfma_f32_16x16x32_bf16 v[124:127], v[170:173], v[202:205], v[124:127]
	v_mfma_f32_16x16x32_bf16 v[120:123], v[178:181], v[202:205], v[120:123]
	v_mfma_f32_16x16x32_bf16 v[116:119], v[170:173], v[210:213], v[116:119]
	v_mfma_f32_16x16x32_bf16 v[112:115], v[178:181], v[210:213], v[112:115]
	v_mfma_f32_16x16x32_bf16 v[108:111], v[170:173], v[224:227], v[108:111]
	v_mfma_f32_16x16x32_bf16 v[104:107], v[178:181], v[224:227], v[104:107]
	v_mfma_f32_16x16x32_bf16 v[100:103], v[170:173], v[232:235], v[100:103]
	v_mfma_f32_16x16x32_bf16 v[96:99], v[178:181], v[232:235], v[96:99]
	v_mfma_f32_16x16x32_bf16 v[92:95], v[182:185], v[198:201], v[92:95]
	v_mfma_f32_16x16x32_bf16 v[88:91], v[190:193], v[198:201], v[88:91]
	v_mfma_f32_16x16x32_bf16 v[84:87], v[182:185], v[206:209], v[84:87]
	v_mfma_f32_16x16x32_bf16 v[80:83], v[190:193], v[206:209], v[80:83]
	v_mfma_f32_16x16x32_bf16 v[76:79], v[182:185], v[220:223], v[76:79]
	v_mfma_f32_16x16x32_bf16 v[72:75], v[190:193], v[220:223], v[72:75]
	v_mfma_f32_16x16x32_bf16 v[68:71], v[182:185], v[228:231], v[68:71]
	v_mfma_f32_16x16x32_bf16 v[64:67], v[190:193], v[228:231], v[64:67]
	v_mfma_f32_16x16x32_bf16 v[92:95], v[186:189], v[202:205], v[92:95]
	v_mfma_f32_16x16x32_bf16 v[88:91], v[194:197], v[202:205], v[88:91]
	v_mfma_f32_16x16x32_bf16 v[84:87], v[186:189], v[210:213], v[84:87]
	v_mfma_f32_16x16x32_bf16 v[80:83], v[194:197], v[210:213], v[80:83]
	v_mfma_f32_16x16x32_bf16 v[76:79], v[186:189], v[224:227], v[76:79]
	v_mfma_f32_16x16x32_bf16 v[72:75], v[194:197], v[224:227], v[72:75]
	v_mfma_f32_16x16x32_bf16 v[68:71], v[186:189], v[232:235], v[68:71]
	s_setprio 0
	v_mfma_f32_16x16x32_bf16 v[64:67], v[194:197], v[232:235], v[64:67]
	s_barrier
	s_add_i32 s75, s75, s65
	s_mov_b32 m0, s75
	ds_read_b128 v[198:201], v147 offset:16384
	ds_read_b128 v[202:205], v147 offset:17408
	ds_read_b128 v[206:209], v147 offset:18432
	ds_read_b128 v[210:213], v147 offset:19456
	ds_read_b128 v[220:223], v147 offset:20480
	ds_read_b128 v[224:227], v147 offset:21504
	ds_read_b128 v[228:231], v147 offset:22528
	ds_read_b128 v[232:235], v147 offset:23552
	global_load_lds_dwordx4 v130, s[54:55]
	s_add_i32 m0, s75, 0x2000
	s_add_u32 s76, s54, 0x80000
	s_addc_u32 s77, s55, 0
	s_add_i32 s75, s78, s65
	global_load_lds_dwordx4 v134, s[54:55]
	s_mov_b32 m0, s75
	s_nop 0
	global_load_lds_dwordx4 v130, s[76:77]
	s_add_i32 m0, s75, 0x2000
	s_nop 0
	global_load_lds_dwordx4 v134, s[76:77]
	s_mov_b32 m0, s15
	s_nop 0
	global_load_lds_dwordx4 v128, s[56:57]
	s_mov_b32 m0, s17
	s_nop 0
	global_load_lds_dwordx4 v132, s[56:57]
	s_waitcnt vmcnt(8)
	s_waitcnt lgkmcnt(0)
	s_setprio 1
	s_barrier
; #define PG8_STAGE(bufoff, gbase, voff) do { _Pragma("unroll") for (int _i = 0; _i < 2; ++_i) \
;         __builtin_amdgcn_global_load_lds((const unsigned*)((const char*)(gbase) + (voff)[_i]), (PG8_LAS unsigned*)(lds + (bufoff) + ldsw + _i * 8192), 16, 0, 0); } while (0)
; #define PG8_LDA(dst, b, h) do { _Pragma("unroll") for (int m = 0; m < 4; ++m) _Pragma("unroll") for (int k = 0; k < 2; ++k) dst[m][k] = *(const PG8_LAS bf16x8*)(lds + PG8_SA(b, h) + aoff + m * 2048 + k * 1024); } while (0)
; #define PG8_LDB(dst, b, h) do { _Pragma("unroll") for (int n = 0; n < 2; ++n) _Pragma("unroll") for (int k = 0; k < 2; ++k) dst[n][k] = *(const PG8_LAS bf16x8*)(lds + PG8_SB(b, h) + boff + n * 2048 + k * 1024); } while (0)
; #define PG8_MMA(ai, bj, At, Bt) do { __builtin_amdgcn_s_setprio(1); _Pragma("unroll") for (int m = 0; m < 4; ++m) _Pragma("unroll") for (int n = 0; n < 2; ++n) _Pragma("unroll") for (int k = 0; k < 2; ++k) \
;         acc[ai][bj][m][n] = __builtin_amdgcn_mfma_f32_16x16x32_bf16(Bt[n][k], At[m][k], acc[ai][bj][m][n], 0, 0, 0); __builtin_amdgcn_s_setprio(0); } while (0)
; #define PG8_WAIT_V(n) asm volatile("s_waitcnt vmcnt(" #n ")" ::: "memory")
; #define PG8_WAIT_L(n) asm volatile("s_waitcnt lgkmcnt(" #n ")" ::: "memory")
; #define PG8_BAR __builtin_amdgcn_s_barrier()
; #define PG8_SCHED __builtin_amdgcn_sched_barrier(0)
; template <class Epi, class Sched, bool ALIGN_EPI = false, bool SP2 = false>
; __device__ __forceinline__ void gemm_phase(PG8_LAS unsigned char* lds, const Gemm g, const Sched& S, const Epi& E) {
;     ...
;             PG8_WAIT_V(8); PG8_WAIT_L(0); PG8_BAR; PG8_MMA(1, 0, At, B0); PG8_MMA(1, 1, At, B1); PG8_BAR; PG8_SCHED;
;             PG8_LDB(B0, 1, 0); PG8_LDB(B1, 1, 1); PG8_SCHED; PG8_LDA(At, 1, 0); PG8_STAGE(PG8_SA(0, 1), a2 + hstep, voffA);
;             PG8_WAIT_V(8); PG8_WAIT_L(0); PG8_BAR; PG8_MMA(0, 0, At, B0); PG8_MMA(0, 1, At, B1); PG8_BAR; PG8_SCHED;
	v_mfma_f32_16x16x32_bf16 v[60:63], v[148:151], v[198:201], v[60:63]
	v_mfma_f32_16x16x32_bf16 v[56:59], v[174:177], v[198:201], v[56:59]
	v_mfma_f32_16x16x32_bf16 v[52:55], v[148:151], v[206:209], v[52:55]
	v_mfma_f32_16x16x32_bf16 v[48:51], v[174:177], v[206:209], v[48:51]
	v_mfma_f32_16x16x32_bf16 v[44:47], v[148:151], v[220:223], v[44:47]
	v_mfma_f32_16x16x32_bf16 v[40:43], v[174:177], v[220:223], v[40:43]
	v_mfma_f32_16x16x32_bf16 v[36:39], v[148:151], v[228:231], v[36:39]
	v_mfma_f32_16x16x32_bf16 v[32:35], v[174:177], v[228:231], v[32:35]
	v_mfma_f32_16x16x32_bf16 v[60:63], v[170:173], v[202:205], v[60:63]
	v_mfma_f32_16x16x32_bf16 v[56:59], v[178:181], v[202:205], v[56:59]
	v_mfma_f32_16x16x32_bf16 v[52:55], v[170:173], v[210:213], v[52:55]
	v_mfma_f32_16x16x32_bf16 v[48:51], v[178:181], v[210:213], v[48:51]
	v_mfma_f32_16x16x32_bf16 v[44:47], v[170:173], v[224:227], v[44:47]
	v_mfma_f32_16x16x32_bf16 v[40:43], v[178:181], v[224:227], v[40:43]
	v_mfma_f32_16x16x32_bf16 v[36:39], v[170:173], v[232:235], v[36:39]
	v_mfma_f32_16x16x32_bf16 v[32:35], v[178:181], v[232:235], v[32:35]
	v_mfma_f32_16x16x32_bf16 v[28:31], v[182:185], v[198:201], v[28:31]
	v_mfma_f32_16x16x32_bf16 v[24:27], v[190:193], v[198:201], v[24:27]
	v_mfma_f32_16x16x32_bf16 v[20:23], v[182:185], v[206:209], v[20:23]
	v_mfma_f32_16x16x32_bf16 v[16:19], v[190:193], v[206:209], v[16:19]
	v_mfma_f32_16x16x32_bf16 v[12:15], v[182:185], v[220:223], v[12:15]
	v_mfma_f32_16x16x32_bf16 v[8:11], v[190:193], v[220:223], v[8:11]
	v_mfma_f32_16x16x32_bf16 v[4:7], v[182:185], v[228:231], v[4:7]
	v_mfma_f32_16x16x32_bf16 v[0:3], v[190:193], v[228:231], v[0:3]
	v_mfma_f32_16x16x32_bf16 v[28:31], v[186:189], v[202:205], v[28:31]
	v_mfma_f32_16x16x32_bf16 v[24:27], v[194:197], v[202:205], v[24:27]
	v_mfma_f32_16x16x32_bf16 v[20:23], v[186:189], v[210:213], v[20:23]
	v_mfma_f32_16x16x32_bf16 v[16:19], v[194:197], v[210:213], v[16:19]
	v_mfma_f32_16x16x32_bf16 v[12:15], v[186:189], v[224:227], v[12:15]
	v_mfma_f32_16x16x32_bf16 v[8:11], v[194:197], v[224:227], v[8:11]
	v_mfma_f32_16x16x32_bf16 v[4:7], v[186:189], v[232:235], v[4:7]
	s_setprio 0
	v_mfma_f32_16x16x32_bf16 v[0:3], v[194:197], v[232:235], v[0:3]
	s_barrier
	s_add_i32 s75, 0, 0x18000
	v_add_u32_e32 v152, s75, v145
	s_add_i32 s76, 0, 0x1c000
	ds_read_b128 v[148:151], v152
	ds_read_b128 v[170:173], v152 offset:1024
	ds_read_b128 v[174:177], v152 offset:2048
	ds_read_b128 v[178:181], v152 offset:3072
	v_add_u32_e32 v152, s76, v145
	ds_read_b128 v[182:185], v152
	ds_read_b128 v[186:189], v152 offset:1024
	ds_read_b128 v[190:193], v152 offset:2048
	ds_read_b128 v[194:197], v152 offset:3072
	s_add_u32 s56, s56, 0x80000
	s_addc_u32 s57, s57, 0
	s_mov_b32 m0, s68
	ds_read_b128 v[198:201], v147 offset:32768
	ds_read_b128 v[202:205], v147 offset:33792
	ds_read_b128 v[206:209], v147 offset:34816
	ds_read_b128 v[210:213], v147 offset:35840
	ds_read_b128 v[220:223], v147 offset:36864
	ds_read_b128 v[224:227], v147 offset:37888
	ds_read_b128 v[228:231], v147 offset:38912
	ds_read_b128 v[232:235], v147 offset:39936
	global_load_lds_dwordx4 v128, s[56:57]
	s_mov_b32 m0, s69
	s_nop 0
	global_load_lds_dwordx4 v132, s[56:57]
	s_waitcnt vmcnt(8)
	s_waitcnt lgkmcnt(0)
	s_setprio 1
	s_barrier
	v_mfma_f32_16x16x32_bf16 v[124:127], v[148:151], v[198:201], v[124:127]
	v_mfma_f32_16x16x32_bf16 v[120:123], v[174:177], v[198:201], v[120:123]
	v_mfma_f32_16x16x32_bf16 v[116:119], v[148:151], v[206:209], v[116:119]
	v_mfma_f32_16x16x32_bf16 v[112:115], v[174:177], v[206:209], v[112:115]
	v_mfma_f32_16x16x32_bf16 v[108:111], v[148:151], v[220:223], v[108:111]
	v_mfma_f32_16x16x32_bf16 v[104:107], v[174:177], v[220:223], v[104:107]
	v_mfma_f32_16x16x32_bf16 v[100:103], v[148:151], v[228:231], v[100:103]
	v_mfma_f32_16x16x32_bf16 v[96:99], v[174:177], v[228:231], v[96:99]
	v_mfma_f32_16x16x32_bf16 v[124:127], v[170:173], v[202:205], v[124:127]
	v_mfma_f32_16x16x32_bf16 v[120:123], v[178:181], v[202:205], v[120:123]
	v_mfma_f32_16x16x32_bf16 v[116:119], v[170:173], v[210:213], v[116:119]
	v_mfma_f32_16x16x32_bf16 v[112:115], v[178:181], v[210:213], v[112:115]
	v_mfma_f32_16x16x32_bf16 v[108:111], v[170:173], v[224:227], v[108:111]
	v_mfma_f32_16x16x32_bf16 v[104:107], v[178:181], v[224:227], v[104:107]
	v_mfma_f32_16x16x32_bf16 v[100:103], v[170:173], v[232:235], v[100:103]
	v_mfma_f32_16x16x32_bf16 v[96:99], v[178:181], v[232:235], v[96:99]
	v_mfma_f32_16x16x32_bf16 v[92:95], v[182:185], v[198:201], v[92:95]
	v_mfma_f32_16x16x32_bf16 v[88:91], v[190:193], v[198:201], v[88:91]
	v_mfma_f32_16x16x32_bf16 v[84:87], v[182:185], v[206:209], v[84:87]
	v_mfma_f32_16x16x32_bf16 v[80:83], v[190:193], v[206:209], v[80:83]
	v_mfma_f32_16x16x32_bf16 v[76:79], v[182:185], v[220:223], v[76:79]
	v_mfma_f32_16x16x32_bf16 v[72:75], v[190:193], v[220:223], v[72:75]
	v_mfma_f32_16x16x32_bf16 v[68:71], v[182:185], v[228:231], v[68:71]
	v_mfma_f32_16x16x32_bf16 v[64:67], v[190:193], v[228:231], v[64:67]
	v_mfma_f32_16x16x32_bf16 v[92:95], v[186:189], v[202:205], v[92:95]
	v_mfma_f32_16x16x32_bf16 v[88:91], v[194:197], v[202:205], v[88:91]
	v_mfma_f32_16x16x32_bf16 v[84:87], v[186:189], v[210:213], v[84:87]
	v_mfma_f32_16x16x32_bf16 v[80:83], v[194:197], v[210:213], v[80:83]
	v_mfma_f32_16x16x32_bf16 v[76:79], v[186:189], v[224:227], v[76:79]
	v_mfma_f32_16x16x32_bf16 v[72:75], v[194:197], v[224:227], v[72:75]
	v_mfma_f32_16x16x32_bf16 v[68:71], v[186:189], v[232:235], v[68:71]
	s_setprio 0
	v_mfma_f32_16x16x32_bf16 v[64:67], v[194:197], v[232:235], v[64:67]
	s_barrier
; #define PG8_STAGE(bufoff, gbase, voff) do { _Pragma("unroll") for (int _i = 0; _i < 2; ++_i) \
;         __builtin_amdgcn_global_load_lds((const unsigned*)((const char*)(gbase) + (voff)[_i]), (PG8_LAS unsigned*)(lds + (bufoff) + ldsw + _i * 8192), 16, 0, 0); } while (0)
; #define PG8_LDA(dst, b, h) do { _Pragma("unroll") for (int m = 0; m < 4; ++m) _Pragma("unroll") for (int k = 0; k < 2; ++k) dst[m][k] = *(const PG8_LAS bf16x8*)(lds + PG8_SA(b, h) + aoff + m * 2048 + k * 1024); } while (0)
; #define PG8_MMA(ai, bj, At, Bt) do { __builtin_amdgcn_s_setprio(1); _Pragma("unroll") for (int m = 0; m < 4; ++m) _Pragma("unroll") for (int n = 0; n < 2; ++n) _Pragma("unroll") for (int k = 0; k < 2; ++k) \
;         acc[ai][bj][m][n] = __builtin_amdgcn_mfma_f32_16x16x32_bf16(Bt[n][k], At[m][k], acc[ai][bj][m][n], 0, 0, 0); __builtin_amdgcn_s_setprio(0); } while (0)
; #define PG8_WAIT_V(n) asm volatile("s_waitcnt vmcnt(" #n ")" ::: "memory")
; #define PG8_WAIT_L(n) asm volatile("s_waitcnt lgkmcnt(" #n ")" ::: "memory")
; #define PG8_BAR __builtin_amdgcn_s_barrier()
; #define PG8_SCHED __builtin_amdgcn_sched_barrier(0)
; template <class Epi, class Sched, bool ALIGN_EPI = false, bool SP2 = false>
; __device__ __forceinline__ void gemm_phase(PG8_LAS unsigned char* lds, const Gemm g, const Sched& S, const Epi& E) {
;     ...
;         for (int t = 0; t < nt; t += 2) {
;             const bool last = (t == nt - 2);
;             const char* a1 = cA + (size_t)(t + 1) * kstep;
;             const char* a2 = last ? nA : cA + (size_t)(t + 2) * kstep; const char* b2 = last ? nB : cB + (size_t)(t + 2) * kstep;
;     ...
;             PG8_LDA(At, 1, 1); PG8_STAGE(PG8_SB(1, 0), b3, voffB); PG8_STAGE(PG8_SB(1, 1), b3 + hstep, voffB); PG8_STAGE(PG8_SA(1, 0), a3, voffA);
;             PG8_WAIT_V(8); PG8_WAIT_L(0); PG8_BAR; PG8_MMA(1, 0, At, B0); PG8_MMA(1, 1, At, B1); PG8_BAR; PG8_SCHED;
	s_add_i32 s78, s75, s65
	s_add_u32 s54, s54, 0x80
	s_addc_u32 s55, s55, 0
	s_mov_b32 m0, s78
	ds_read_b128 v[198:201], v147 offset:49152
	ds_read_b128 v[202:205], v147 offset:50176
	ds_read_b128 v[206:209], v147 offset:51200
	ds_read_b128 v[210:213], v147 offset:52224
	ds_read_b128 v[220:223], v147 offset:53248
	ds_read_b128 v[224:227], v147 offset:54272
	ds_read_b128 v[228:231], v147 offset:55296
	ds_read_b128 v[232:235], v147 offset:56320
	global_load_lds_dwordx4 v130, s[54:55]
	s_add_i32 m0, s78, 0x2000
	s_add_i32 s78, s76, s65
	global_load_lds_dwordx4 v134, s[54:55]
	s_add_u32 s54, s54, 0x80000
	s_addc_u32 s55, s55, 0
	s_mov_b32 m0, s78
	s_nop 0
	global_load_lds_dwordx4 v130, s[54:55]
	s_add_i32 m0, s78, 0x2000
	s_sub_u32 s56, s56, 0x7ff80
	s_subb_u32 s57, s57, 0
	global_load_lds_dwordx4 v134, s[54:55]
	s_mov_b32 m0, s70
	s_nop 0
	global_load_lds_dwordx4 v128, s[56:57]
	s_mov_b32 m0, s71
	s_nop 0
	global_load_lds_dwordx4 v132, s[56:57]
	s_waitcnt vmcnt(8)
	s_waitcnt lgkmcnt(0)
	s_setprio 1
	s_barrier
	v_mfma_f32_16x16x32_bf16 v[60:63], v[148:151], v[198:201], v[60:63]
	v_mfma_f32_16x16x32_bf16 v[56:59], v[174:177], v[198:201], v[56:59]
	v_mfma_f32_16x16x32_bf16 v[52:55], v[148:151], v[206:209], v[52:55]
	v_mfma_f32_16x16x32_bf16 v[48:51], v[174:177], v[206:209], v[48:51]
	v_mfma_f32_16x16x32_bf16 v[44:47], v[148:151], v[220:223], v[44:47]
	v_mfma_f32_16x16x32_bf16 v[40:43], v[174:177], v[220:223], v[40:43]
	v_mfma_f32_16x16x32_bf16 v[36:39], v[148:151], v[228:231], v[36:39]
	v_mfma_f32_16x16x32_bf16 v[32:35], v[174:177], v[228:231], v[32:35]
	v_mfma_f32_16x16x32_bf16 v[60:63], v[170:173], v[202:205], v[60:63]
	v_mfma_f32_16x16x32_bf16 v[56:59], v[178:181], v[202:205], v[56:59]
	v_mfma_f32_16x16x32_bf16 v[52:55], v[170:173], v[210:213], v[52:55]
	v_mfma_f32_16x16x32_bf16 v[48:51], v[178:181], v[210:213], v[48:51]
	v_mfma_f32_16x16x32_bf16 v[44:47], v[170:173], v[224:227], v[44:47]
	v_mfma_f32_16x16x32_bf16 v[40:43], v[178:181], v[224:227], v[40:43]
	v_mfma_f32_16x16x32_bf16 v[36:39], v[170:173], v[232:235], v[36:39]
	v_mfma_f32_16x16x32_bf16 v[32:35], v[178:181], v[232:235], v[32:35]
	v_mfma_f32_16x16x32_bf16 v[28:31], v[182:185], v[198:201], v[28:31]
	v_mfma_f32_16x16x32_bf16 v[24:27], v[190:193], v[198:201], v[24:27]
	v_mfma_f32_16x16x32_bf16 v[20:23], v[182:185], v[206:209], v[20:23]
	v_mfma_f32_16x16x32_bf16 v[16:19], v[190:193], v[206:209], v[16:19]
	v_mfma_f32_16x16x32_bf16 v[12:15], v[182:185], v[220:223], v[12:15]
	v_mfma_f32_16x16x32_bf16 v[8:11], v[190:193], v[220:223], v[8:11]
	v_mfma_f32_16x16x32_bf16 v[4:7], v[182:185], v[228:231], v[4:7]
	v_mfma_f32_16x16x32_bf16 v[0:3], v[190:193], v[228:231], v[0:3]
	v_mfma_f32_16x16x32_bf16 v[28:31], v[186:189], v[202:205], v[28:31]
	v_mfma_f32_16x16x32_bf16 v[24:27], v[194:197], v[202:205], v[24:27]
	v_mfma_f32_16x16x32_bf16 v[20:23], v[186:189], v[210:213], v[20:23]
	v_mfma_f32_16x16x32_bf16 v[16:19], v[194:197], v[210:213], v[16:19]
	v_mfma_f32_16x16x32_bf16 v[12:15], v[186:189], v[224:227], v[12:15]
	v_mfma_f32_16x16x32_bf16 v[8:11], v[194:197], v[224:227], v[8:11]
	v_mfma_f32_16x16x32_bf16 v[4:7], v[186:189], v[232:235], v[4:7]
	s_setprio 0
	v_mfma_f32_16x16x32_bf16 v[0:3], v[194:197], v[232:235], v[0:3]
	s_barrier
	s_add_i32 s74, s74, 2
	s_add_u32 s52, s52, 0x100
	s_addc_u32 s53, s53, 0
	s_cmp_gt_u32 s74, 29
	s_cbranch_scc0 .LBB0_431
	s_and_b64 vcc, exec, s[26:27]
	s_cbranch_vccz .LBB0_434
	s_barrier
